# v44: v26 with one static s_setprio 1 for waves 4-7 per GEMM phase instead of hipcc's per-segment priority toggling in the six K loops
# speedup vs baseline: 1.0068x; 1.0068x over previous
.LBB0_105:
	s_cmp_lt_i32 s90, 2
	s_cselect_b64 s[0:1], -1, 0
	s_cmp_gt_i32 s91, 1
	s_cselect_b64 s[2:3], -1, 0
	s_and_b64 s[0:1], s[0:1], s[2:3]
	s_andn2_b64 vcc, exec, s[0:1]
	s_cbranch_vccnz .LBB0_190
	s_cmpk_lt_u32 s80, 0x100
	s_cbranch_scc1 .Lprio_skip_0
	s_setprio 1
.Lprio_skip_0:
	s_cmpk_gt_i32 s24, 0x5ab
	v_readfirstlane_b32 s3, v0
	v_mbcnt_lo_u32_b32 v1, -1, 0
	v_mbcnt_hi_u32_b32 v1, -1, v1
	s_cbranch_scc1 .LBB0_130
	s_ashr_i32 s25, s24, 31
	s_lshr_b32 s0, s25, 29
	s_add_i32 s4, s24, s0
	s_and_b32 s0, s4, -8
	s_sub_i32 s5, s24, s0
	s_cmp_gt_i32 s5, 3
	s_cbranch_scc0 .LBB0_109
	s_mul_i32 s0, s5, 0xb5
	s_add_i32 s2, s0, 4
	s_cbranch_execz .LBB0_110
	s_branch .LBB0_111

.LBB0_123:
	ds_read_b128 v[146:149], v153
	ds_read_b128 v[156:159], v153 offset:1024
	ds_read_b128 v[160:163], v153 offset:2048
	ds_read_b128 v[164:167], v153 offset:3072
	ds_read_b128 v[168:171], v154
	ds_read_b128 v[172:175], v154 offset:1024
	ds_read_b128 v[176:179], v154 offset:2048
	ds_read_b128 v[180:183], v154 offset:3072
	s_add_u32 s22, s20, 0xfffc0080
	s_addc_u32 s23, s21, -1
	s_cmp_eq_u32 s64, 12
	s_cselect_b32 s31, s13, s23
	s_cselect_b32 s30, s48, s22
	s_cselect_b32 s23, s11, s51
	s_cselect_b32 s22, s49, s50
	v_lshl_add_u64 v[216:217], s[20:21], 0, v[138:139]
	s_add_i32 m0, s37, 0xc000
	ds_read_b128 v[184:187], v155
	ds_read_b128 v[188:191], v155 offset:1024
	ds_read_b128 v[192:195], v155 offset:2048
	ds_read_b128 v[196:199], v155 offset:3072
	ds_read_b128 v[200:203], v155 offset:4096
	ds_read_b128 v[204:207], v155 offset:5120
	ds_read_b128 v[208:211], v155 offset:6144
	ds_read_b128 v[212:215], v155 offset:7168
	global_load_lds_dwordx4 v[216:217], off
	v_lshl_add_u64 v[216:217], s[20:21], 0, v[140:141]
	s_add_i32 m0, s37, 0xe000
	s_nop 0
	global_load_lds_dwordx4 v[216:217], off
	s_waitcnt vmcnt(8)
	s_waitcnt lgkmcnt(0)
	s_barrier
	s_waitcnt lgkmcnt(0)
	v_mfma_f32_16x16x32_bf16 v[126:129], v[146:149], v[184:187], v[126:129]
	v_mfma_f32_16x16x32_bf16 v[118:121], v[160:163], v[184:187], v[118:121]
	v_mfma_f32_16x16x32_bf16 v[110:113], v[146:149], v[192:195], v[110:113]
	v_mfma_f32_16x16x32_bf16 v[102:105], v[160:163], v[192:195], v[102:105]
	v_mfma_f32_16x16x32_bf16 v[94:97], v[146:149], v[200:203], v[94:97]
	v_mfma_f32_16x16x32_bf16 v[86:89], v[160:163], v[200:203], v[86:89]
	v_mfma_f32_16x16x32_bf16 v[78:81], v[146:149], v[208:211], v[78:81]
	v_mfma_f32_16x16x32_bf16 v[70:73], v[160:163], v[208:211], v[70:73]
	v_mfma_f32_16x16x32_bf16 v[126:129], v[156:159], v[188:191], v[126:129]
	v_mfma_f32_16x16x32_bf16 v[118:121], v[164:167], v[188:191], v[118:121]
	v_mfma_f32_16x16x32_bf16 v[110:113], v[156:159], v[196:199], v[110:113]
	v_mfma_f32_16x16x32_bf16 v[102:105], v[164:167], v[196:199], v[102:105]
	v_mfma_f32_16x16x32_bf16 v[94:97], v[156:159], v[204:207], v[94:97]
	v_mfma_f32_16x16x32_bf16 v[86:89], v[164:167], v[204:207], v[86:89]
	v_mfma_f32_16x16x32_bf16 v[78:81], v[156:159], v[212:215], v[78:81]
	v_mfma_f32_16x16x32_bf16 v[70:73], v[164:167], v[212:215], v[70:73]
	v_mfma_f32_16x16x32_bf16 v[122:125], v[168:171], v[184:187], v[122:125]
	v_mfma_f32_16x16x32_bf16 v[114:117], v[176:179], v[184:187], v[114:117]
	v_mfma_f32_16x16x32_bf16 v[106:109], v[168:171], v[192:195], v[106:109]
	v_mfma_f32_16x16x32_bf16 v[98:101], v[176:179], v[192:195], v[98:101]
	v_mfma_f32_16x16x32_bf16 v[90:93], v[168:171], v[200:203], v[90:93]
	v_mfma_f32_16x16x32_bf16 v[82:85], v[176:179], v[200:203], v[82:85]
	v_mfma_f32_16x16x32_bf16 v[74:77], v[168:171], v[208:211], v[74:77]
	v_mfma_f32_16x16x32_bf16 v[66:69], v[176:179], v[208:211], v[66:69]
	v_mfma_f32_16x16x32_bf16 v[122:125], v[172:175], v[188:191], v[122:125]
	v_mfma_f32_16x16x32_bf16 v[114:117], v[180:183], v[188:191], v[114:117]
	v_mfma_f32_16x16x32_bf16 v[106:109], v[172:175], v[196:199], v[106:109]
	v_mfma_f32_16x16x32_bf16 v[98:101], v[180:183], v[196:199], v[98:101]
	v_mfma_f32_16x16x32_bf16 v[90:93], v[172:175], v[204:207], v[90:93]
	v_mfma_f32_16x16x32_bf16 v[82:85], v[180:183], v[204:207], v[82:85]
	v_mfma_f32_16x16x32_bf16 v[74:77], v[172:175], v[212:215], v[74:77]
	v_mfma_f32_16x16x32_bf16 v[66:69], v[180:183], v[212:215], v[66:69]
	s_barrier
	s_add_i32 s65, s45, s36
	v_lshl_add_u64 v[216:217], s[22:23], 0, v[132:133]
	s_mov_b32 m0, s65
	ds_read_b128 v[184:187], v155 offset:16384
	ds_read_b128 v[188:191], v155 offset:17408
	ds_read_b128 v[192:195], v155 offset:18432
	ds_read_b128 v[196:199], v155 offset:19456
	ds_read_b128 v[200:203], v155 offset:20480
	ds_read_b128 v[204:207], v155 offset:21504
	ds_read_b128 v[208:211], v155 offset:22528
	ds_read_b128 v[212:215], v155 offset:23552
	global_load_lds_dwordx4 v[216:217], off
	s_add_i32 m0, s65, 0x2000
	s_add_u32 s68, s22, 0x40000
	v_lshl_add_u64 v[218:219], s[22:23], 0, v[136:137]
	s_addc_u32 s69, s23, 0
	s_add_i32 s65, s46, s36
	global_load_lds_dwordx4 v[218:219], off
	v_lshl_add_u64 v[220:221], s[68:69], 0, v[132:133]
	s_mov_b32 m0, s65
	v_lshl_add_u64 v[222:223], s[30:31], 0, v[134:135]
	global_load_lds_dwordx4 v[220:221], off
	v_lshl_add_u64 v[220:221], s[68:69], 0, v[136:137]
	s_add_i32 m0, s65, 0x2000
	s_nop 0
	global_load_lds_dwordx4 v[220:221], off
	v_lshl_add_u64 v[220:221], s[30:31], 0, v[130:131]
	s_mov_b32 m0, s37
	s_nop 0
	global_load_lds_dwordx4 v[220:221], off
	s_mov_b32 m0, s38
	s_nop 0
	global_load_lds_dwordx4 v[222:223], off
	s_waitcnt vmcnt(8)
	s_waitcnt lgkmcnt(0)
	s_barrier
	s_waitcnt lgkmcnt(0)
	v_mfma_f32_16x16x32_bf16 v[62:65], v[146:149], v[184:187], v[62:65]
	v_mfma_f32_16x16x32_bf16 v[54:57], v[160:163], v[184:187], v[54:57]
	v_mfma_f32_16x16x32_bf16 v[46:49], v[146:149], v[192:195], v[46:49]
	v_mfma_f32_16x16x32_bf16 v[38:41], v[160:163], v[192:195], v[38:41]
	v_mfma_f32_16x16x32_bf16 v[30:33], v[146:149], v[200:203], v[30:33]
	v_mfma_f32_16x16x32_bf16 v[22:25], v[160:163], v[200:203], v[22:25]
	v_mfma_f32_16x16x32_bf16 v[14:17], v[146:149], v[208:211], v[14:17]
	v_mfma_f32_16x16x32_bf16 v[6:9], v[160:163], v[208:211], v[6:9]
	v_mfma_f32_16x16x32_bf16 v[62:65], v[156:159], v[188:191], v[62:65]
	v_mfma_f32_16x16x32_bf16 v[54:57], v[164:167], v[188:191], v[54:57]
	v_mfma_f32_16x16x32_bf16 v[46:49], v[156:159], v[196:199], v[46:49]
	v_mfma_f32_16x16x32_bf16 v[38:41], v[164:167], v[196:199], v[38:41]
	v_mfma_f32_16x16x32_bf16 v[30:33], v[156:159], v[204:207], v[30:33]
	v_mfma_f32_16x16x32_bf16 v[22:25], v[164:167], v[204:207], v[22:25]
	v_mfma_f32_16x16x32_bf16 v[14:17], v[156:159], v[212:215], v[14:17]
	v_mfma_f32_16x16x32_bf16 v[6:9], v[164:167], v[212:215], v[6:9]
	v_mfma_f32_16x16x32_bf16 v[58:61], v[168:171], v[184:187], v[58:61]
	v_mfma_f32_16x16x32_bf16 v[50:53], v[176:179], v[184:187], v[50:53]
	v_mfma_f32_16x16x32_bf16 v[42:45], v[168:171], v[192:195], v[42:45]
	v_mfma_f32_16x16x32_bf16 v[34:37], v[176:179], v[192:195], v[34:37]
	v_mfma_f32_16x16x32_bf16 v[26:29], v[168:171], v[200:203], v[26:29]
	v_mfma_f32_16x16x32_bf16 v[18:21], v[176:179], v[200:203], v[18:21]
	v_mfma_f32_16x16x32_bf16 v[10:13], v[168:171], v[208:211], v[10:13]
	v_mfma_f32_16x16x32_bf16 v[2:5], v[176:179], v[208:211], v[2:5]
	v_mfma_f32_16x16x32_bf16 v[58:61], v[172:175], v[188:191], v[58:61]
	v_mfma_f32_16x16x32_bf16 v[50:53], v[180:183], v[188:191], v[50:53]
	v_mfma_f32_16x16x32_bf16 v[42:45], v[172:175], v[196:199], v[42:45]
	v_mfma_f32_16x16x32_bf16 v[34:37], v[180:183], v[196:199], v[34:37]
	v_mfma_f32_16x16x32_bf16 v[26:29], v[172:175], v[204:207], v[26:29]
	v_mfma_f32_16x16x32_bf16 v[18:21], v[180:183], v[204:207], v[18:21]
	v_mfma_f32_16x16x32_bf16 v[10:13], v[172:175], v[212:215], v[10:13]
	v_mfma_f32_16x16x32_bf16 v[2:5], v[180:183], v[212:215], v[2:5]
	s_barrier
	s_add_i32 s65, 0, 0x18000
	s_add_i32 s68, 0, 0x1c000
	v_add_u32_e32 v164, s65, v151
	v_add_u32_e32 v180, s68, v151
	ds_read_b128 v[146:149], v164
	ds_read_b128 v[156:159], v164 offset:1024
	ds_read_b128 v[160:163], v164 offset:2048
	ds_read_b128 v[164:167], v164 offset:3072
	ds_read_b128 v[168:171], v180
	ds_read_b128 v[172:175], v180 offset:1024
	ds_read_b128 v[176:179], v180 offset:2048
	ds_read_b128 v[180:183], v180 offset:3072
	s_add_u32 s30, s30, 0x40000
	s_addc_u32 s31, s31, 0
	s_mov_b32 m0, s39
	v_lshl_add_u64 v[224:225], s[30:31], 0, v[130:131]
	ds_read_b128 v[184:187], v155 offset:32768
	ds_read_b128 v[188:191], v155 offset:33792
	ds_read_b128 v[192:195], v155 offset:34816
	ds_read_b128 v[196:199], v155 offset:35840
	ds_read_b128 v[200:203], v155 offset:36864
	ds_read_b128 v[204:207], v155 offset:37888
	ds_read_b128 v[208:211], v155 offset:38912
	ds_read_b128 v[212:215], v155 offset:39936
	global_load_lds_dwordx4 v[224:225], off
	v_lshl_add_u64 v[224:225], s[30:31], 0, v[134:135]
	s_mov_b32 m0, s40
	s_nop 0
	global_load_lds_dwordx4 v[224:225], off
	s_waitcnt vmcnt(8)
	s_waitcnt lgkmcnt(0)
	s_barrier
	s_waitcnt lgkmcnt(0)
	v_mfma_f32_16x16x32_bf16 v[126:129], v[146:149], v[184:187], v[126:129]
	v_mfma_f32_16x16x32_bf16 v[118:121], v[160:163], v[184:187], v[118:121]
	v_mfma_f32_16x16x32_bf16 v[110:113], v[146:149], v[192:195], v[110:113]
	v_mfma_f32_16x16x32_bf16 v[102:105], v[160:163], v[192:195], v[102:105]
	v_mfma_f32_16x16x32_bf16 v[94:97], v[146:149], v[200:203], v[94:97]
	v_mfma_f32_16x16x32_bf16 v[86:89], v[160:163], v[200:203], v[86:89]
	v_mfma_f32_16x16x32_bf16 v[78:81], v[146:149], v[208:211], v[78:81]
	v_mfma_f32_16x16x32_bf16 v[70:73], v[160:163], v[208:211], v[70:73]
	v_mfma_f32_16x16x32_bf16 v[126:129], v[156:159], v[188:191], v[126:129]
	v_mfma_f32_16x16x32_bf16 v[118:121], v[164:167], v[188:191], v[118:121]
	v_mfma_f32_16x16x32_bf16 v[110:113], v[156:159], v[196:199], v[110:113]
	v_mfma_f32_16x16x32_bf16 v[102:105], v[164:167], v[196:199], v[102:105]
	v_mfma_f32_16x16x32_bf16 v[94:97], v[156:159], v[204:207], v[94:97]
	v_mfma_f32_16x16x32_bf16 v[86:89], v[164:167], v[204:207], v[86:89]
	v_mfma_f32_16x16x32_bf16 v[78:81], v[156:159], v[212:215], v[78:81]
	v_mfma_f32_16x16x32_bf16 v[70:73], v[164:167], v[212:215], v[70:73]
	v_mfma_f32_16x16x32_bf16 v[122:125], v[168:171], v[184:187], v[122:125]
	v_mfma_f32_16x16x32_bf16 v[114:117], v[176:179], v[184:187], v[114:117]
	v_mfma_f32_16x16x32_bf16 v[106:109], v[168:171], v[192:195], v[106:109]
	v_mfma_f32_16x16x32_bf16 v[98:101], v[176:179], v[192:195], v[98:101]
	v_mfma_f32_16x16x32_bf16 v[90:93], v[168:171], v[200:203], v[90:93]
	v_mfma_f32_16x16x32_bf16 v[82:85], v[176:179], v[200:203], v[82:85]
	v_mfma_f32_16x16x32_bf16 v[74:77], v[168:171], v[208:211], v[74:77]
	v_mfma_f32_16x16x32_bf16 v[66:69], v[176:179], v[208:211], v[66:69]
	v_mfma_f32_16x16x32_bf16 v[122:125], v[172:175], v[188:191], v[122:125]
	v_mfma_f32_16x16x32_bf16 v[114:117], v[180:183], v[188:191], v[114:117]
	v_mfma_f32_16x16x32_bf16 v[106:109], v[172:175], v[196:199], v[106:109]
	v_mfma_f32_16x16x32_bf16 v[98:101], v[180:183], v[196:199], v[98:101]
	v_mfma_f32_16x16x32_bf16 v[90:93], v[172:175], v[204:207], v[90:93]
	v_mfma_f32_16x16x32_bf16 v[82:85], v[180:183], v[204:207], v[82:85]
	v_mfma_f32_16x16x32_bf16 v[74:77], v[172:175], v[212:215], v[74:77]
	v_mfma_f32_16x16x32_bf16 v[66:69], v[180:183], v[212:215], v[66:69]
	s_barrier
	s_add_i32 s30, s65, s36
	v_lshl_add_u64 v[216:217], v[216:217], 0, s[6:7]
	s_mov_b32 m0, s30
	ds_read_b128 v[184:187], v155 offset:49152
	ds_read_b128 v[188:191], v155 offset:50176
	ds_read_b128 v[192:195], v155 offset:51200
	ds_read_b128 v[196:199], v155 offset:52224
	ds_read_b128 v[200:203], v155 offset:53248
	ds_read_b128 v[204:207], v155 offset:54272
	ds_read_b128 v[208:211], v155 offset:55296
	ds_read_b128 v[212:215], v155 offset:56320
	global_load_lds_dwordx4 v[216:217], off
	s_add_i32 m0, s30, 0x2000
	s_add_u32 s22, s22, 0x40080
	v_lshl_add_u64 v[216:217], v[218:219], 0, s[6:7]
	s_addc_u32 s23, s23, 0
	s_add_i32 s30, s68, s36
	global_load_lds_dwordx4 v[216:217], off
	v_lshl_add_u64 v[216:217], s[22:23], 0, v[132:133]
	s_mov_b32 m0, s30
	s_nop 0
	global_load_lds_dwordx4 v[216:217], off
	v_lshl_add_u64 v[216:217], s[22:23], 0, v[136:137]
	s_add_i32 m0, s30, 0x2000
	s_nop 0
	global_load_lds_dwordx4 v[216:217], off
	v_lshl_add_u64 v[216:217], v[220:221], 0, s[6:7]
	s_mov_b32 m0, s42
	s_nop 0
	global_load_lds_dwordx4 v[216:217], off
	v_lshl_add_u64 v[216:217], v[222:223], 0, s[6:7]
	s_mov_b32 m0, s43
	s_nop 0
	global_load_lds_dwordx4 v[216:217], off
	s_waitcnt vmcnt(8)
	s_waitcnt lgkmcnt(0)
	s_barrier
	s_waitcnt lgkmcnt(0)
	v_mfma_f32_16x16x32_bf16 v[62:65], v[146:149], v[184:187], v[62:65]
	v_mfma_f32_16x16x32_bf16 v[54:57], v[160:163], v[184:187], v[54:57]
	v_mfma_f32_16x16x32_bf16 v[46:49], v[146:149], v[192:195], v[46:49]
	v_mfma_f32_16x16x32_bf16 v[38:41], v[160:163], v[192:195], v[38:41]
	v_mfma_f32_16x16x32_bf16 v[30:33], v[146:149], v[200:203], v[30:33]
	v_mfma_f32_16x16x32_bf16 v[22:25], v[160:163], v[200:203], v[22:25]
	v_mfma_f32_16x16x32_bf16 v[14:17], v[146:149], v[208:211], v[14:17]
	v_mfma_f32_16x16x32_bf16 v[6:9], v[160:163], v[208:211], v[6:9]
	v_mfma_f32_16x16x32_bf16 v[62:65], v[156:159], v[188:191], v[62:65]
	v_mfma_f32_16x16x32_bf16 v[54:57], v[164:167], v[188:191], v[54:57]
	v_mfma_f32_16x16x32_bf16 v[46:49], v[156:159], v[196:199], v[46:49]
	v_mfma_f32_16x16x32_bf16 v[38:41], v[164:167], v[196:199], v[38:41]
	v_mfma_f32_16x16x32_bf16 v[30:33], v[156:159], v[204:207], v[30:33]
	v_mfma_f32_16x16x32_bf16 v[22:25], v[164:167], v[204:207], v[22:25]
	v_mfma_f32_16x16x32_bf16 v[14:17], v[156:159], v[212:215], v[14:17]
	v_mfma_f32_16x16x32_bf16 v[6:9], v[164:167], v[212:215], v[6:9]
	v_mfma_f32_16x16x32_bf16 v[58:61], v[168:171], v[184:187], v[58:61]
	v_mfma_f32_16x16x32_bf16 v[50:53], v[176:179], v[184:187], v[50:53]
	v_mfma_f32_16x16x32_bf16 v[42:45], v[168:171], v[192:195], v[42:45]
	v_mfma_f32_16x16x32_bf16 v[34:37], v[176:179], v[192:195], v[34:37]
	v_mfma_f32_16x16x32_bf16 v[26:29], v[168:171], v[200:203], v[26:29]
	v_mfma_f32_16x16x32_bf16 v[18:21], v[176:179], v[200:203], v[18:21]
	v_mfma_f32_16x16x32_bf16 v[10:13], v[168:171], v[208:211], v[10:13]
	v_mfma_f32_16x16x32_bf16 v[2:5], v[176:179], v[208:211], v[2:5]
	v_mfma_f32_16x16x32_bf16 v[58:61], v[172:175], v[188:191], v[58:61]
	v_mfma_f32_16x16x32_bf16 v[50:53], v[180:183], v[188:191], v[50:53]
	v_mfma_f32_16x16x32_bf16 v[42:45], v[172:175], v[196:199], v[42:45]
	v_mfma_f32_16x16x32_bf16 v[34:37], v[180:183], v[196:199], v[34:37]
	v_mfma_f32_16x16x32_bf16 v[26:29], v[172:175], v[204:207], v[26:29]
	v_mfma_f32_16x16x32_bf16 v[18:21], v[180:183], v[204:207], v[18:21]
	v_mfma_f32_16x16x32_bf16 v[10:13], v[172:175], v[212:215], v[10:13]
	v_mfma_f32_16x16x32_bf16 v[2:5], v[180:183], v[212:215], v[2:5]
	s_barrier
	s_add_i32 s64, s64, 2
	s_add_u32 s20, s20, 0x100
	s_addc_u32 s21, s21, 0
	s_add_u32 s50, s50, 0x100
	s_addc_u32 s51, s51, 0
	s_cmp_gt_u32 s64, 13
	s_cbranch_scc0 .LBB0_123
	s_and_b64 vcc, exec, s[8:9]
	s_cbranch_vccz .LBB0_126
	s_barrier

.LBB0_190:
	s_setprio 0
	s_cmp_lt_i32 s90, 3
	s_cselect_b64 s[0:1], -1, 0
	s_cmp_gt_i32 s91, 2
	s_cselect_b64 s[2:3], -1, 0
	s_and_b64 s[0:1], s[0:1], s[2:3]
	s_andn2_b64 vcc, exec, s[0:1]
	s_cbranch_vccnz .LBB0_286
	s_cmpk_lt_u32 s80, 0x100
	s_cbranch_scc1 .Lprio_skip_1
	s_setprio 1
.Lprio_skip_1:
	s_cmpk_gt_i32 s24, 0xff
	v_readfirstlane_b32 s8, v0
	v_mbcnt_lo_u32_b32 v1, -1, 0
	v_mbcnt_hi_u32_b32 v1, -1, v1
	s_cbranch_scc0 .LBB0_197
	s_mov_b64 s[2:3], 0
	s_cmpk_lt_u32 s24, 0x158
	s_mov_b64 s[0:1], 0
	s_cbranch_scc0 .LBB0_194
	s_and_b32 s0, s24, 0xff
	s_mul_i32 s1, s0, 0x75
	s_lshr_b32 s1, s1, 8
	s_sub_i32 s4, s24, s1
	s_bfe_u32 s4, s4, 0x70001
	s_add_i32 s4, s4, s1
	s_bfe_u32 s1, s4, 0x50003
	s_mul_i32 s4, s1, 11
	s_sub_i32 s4, s24, s4
	s_add_i32 s5, s1, -4
	s_cmp_lt_u32 s0, 44
	s_cselect_b32 s49, s1, s5
	s_cmp_gt_u32 s0, 43
	s_cselect_b32 s50, 0x41, 64
	s_lshl_b32 s0, s4, 2
	s_and_b32 s48, s0, 0xfc
	s_mov_b64 s[0:1], -1
	s_mov_b32 s51, 4
	s_and_b64 vcc, exec, s[2:3]
	s_cbranch_vccz .LBB0_198
	s_branch .LBB0_195

.LBB0_221:
	ds_read_b128 v[144:147], v150
	ds_read_b128 v[154:157], v150 offset:1024
	ds_read_b128 v[158:161], v150 offset:2048
	ds_read_b128 v[162:165], v150 offset:3072
	ds_read_b128 v[166:169], v151
	ds_read_b128 v[170:173], v151 offset:1024
	ds_read_b128 v[174:177], v151 offset:2048
	ds_read_b128 v[178:181], v151 offset:3072
	s_add_u32 s18, s16, 0xfff50080
	s_addc_u32 s19, s17, -1
	s_cmp_eq_u32 s51, s65
	s_cselect_b32 s21, s13, s19
	s_cselect_b32 s20, s12, s18
	s_cselect_b32 s19, s15, s64
	s_cselect_b32 s18, s14, s11
	v_lshl_add_u64 v[214:215], s[16:17], 0, v[138:139]
	s_add_i32 m0, s30, 0xc000
	ds_read_b128 v[182:185], v152
	ds_read_b128 v[186:189], v152 offset:1024
	ds_read_b128 v[190:193], v152 offset:2048
	ds_read_b128 v[194:197], v152 offset:3072
	ds_read_b128 v[198:201], v152 offset:4096
	ds_read_b128 v[202:205], v152 offset:5120
	ds_read_b128 v[206:209], v152 offset:6144
	ds_read_b128 v[210:213], v152 offset:7168
	global_load_lds_dwordx4 v[214:215], off
	v_lshl_add_u64 v[214:215], s[16:17], 0, v[140:141]
	s_add_i32 m0, s30, 0xe000
	s_nop 0
	global_load_lds_dwordx4 v[214:215], off
	s_waitcnt vmcnt(8)
	s_waitcnt lgkmcnt(0)
	s_barrier
	s_waitcnt lgkmcnt(0)
	v_mfma_f32_16x16x32_bf16 v[126:129], v[144:147], v[182:185], v[126:129]
	v_mfma_f32_16x16x32_bf16 v[122:125], v[158:161], v[182:185], v[122:125]
	v_mfma_f32_16x16x32_bf16 v[118:121], v[144:147], v[190:193], v[118:121]
	v_mfma_f32_16x16x32_bf16 v[110:113], v[158:161], v[190:193], v[110:113]
	v_mfma_f32_16x16x32_bf16 v[102:105], v[144:147], v[198:201], v[102:105]
	v_mfma_f32_16x16x32_bf16 v[94:97], v[158:161], v[198:201], v[94:97]
	v_mfma_f32_16x16x32_bf16 v[86:89], v[144:147], v[206:209], v[86:89]
	v_mfma_f32_16x16x32_bf16 v[78:81], v[158:161], v[206:209], v[78:81]
	v_mfma_f32_16x16x32_bf16 v[126:129], v[154:157], v[186:189], v[126:129]
	v_mfma_f32_16x16x32_bf16 v[122:125], v[162:165], v[186:189], v[122:125]
	v_mfma_f32_16x16x32_bf16 v[118:121], v[154:157], v[194:197], v[118:121]
	v_mfma_f32_16x16x32_bf16 v[110:113], v[162:165], v[194:197], v[110:113]
	v_mfma_f32_16x16x32_bf16 v[102:105], v[154:157], v[202:205], v[102:105]
	v_mfma_f32_16x16x32_bf16 v[94:97], v[162:165], v[202:205], v[94:97]
	v_mfma_f32_16x16x32_bf16 v[86:89], v[154:157], v[210:213], v[86:89]
	v_mfma_f32_16x16x32_bf16 v[78:81], v[162:165], v[210:213], v[78:81]
	v_mfma_f32_16x16x32_bf16 v[114:117], v[166:169], v[182:185], v[114:117]
	v_mfma_f32_16x16x32_bf16 v[106:109], v[174:177], v[182:185], v[106:109]
	v_mfma_f32_16x16x32_bf16 v[98:101], v[166:169], v[190:193], v[98:101]
	v_mfma_f32_16x16x32_bf16 v[90:93], v[174:177], v[190:193], v[90:93]
	v_mfma_f32_16x16x32_bf16 v[82:85], v[166:169], v[198:201], v[82:85]
	v_mfma_f32_16x16x32_bf16 v[74:77], v[174:177], v[198:201], v[74:77]
	v_mfma_f32_16x16x32_bf16 v[70:73], v[166:169], v[206:209], v[70:73]
	v_mfma_f32_16x16x32_bf16 v[66:69], v[174:177], v[206:209], v[66:69]
	v_mfma_f32_16x16x32_bf16 v[114:117], v[170:173], v[186:189], v[114:117]
	v_mfma_f32_16x16x32_bf16 v[106:109], v[178:181], v[186:189], v[106:109]
	v_mfma_f32_16x16x32_bf16 v[98:101], v[170:173], v[194:197], v[98:101]
	v_mfma_f32_16x16x32_bf16 v[90:93], v[178:181], v[194:197], v[90:93]
	v_mfma_f32_16x16x32_bf16 v[82:85], v[170:173], v[202:205], v[82:85]
	v_mfma_f32_16x16x32_bf16 v[74:77], v[178:181], v[202:205], v[74:77]
	v_mfma_f32_16x16x32_bf16 v[70:73], v[170:173], v[210:213], v[70:73]
	v_mfma_f32_16x16x32_bf16 v[66:69], v[178:181], v[210:213], v[66:69]
	s_barrier
	s_add_i32 s68, s43, s29
	v_lshl_add_u64 v[214:215], s[18:19], 0, v[132:133]
	s_mov_b32 m0, s68
	ds_read_b128 v[182:185], v152 offset:16384
	ds_read_b128 v[186:189], v152 offset:17408
	ds_read_b128 v[190:193], v152 offset:18432
	ds_read_b128 v[194:197], v152 offset:19456
	ds_read_b128 v[198:201], v152 offset:20480
	ds_read_b128 v[202:205], v152 offset:21504
	ds_read_b128 v[206:209], v152 offset:22528
	ds_read_b128 v[210:213], v152 offset:23552
	global_load_lds_dwordx4 v[214:215], off
	s_add_i32 m0, s68, 0x2000
	s_add_u32 s68, s18, 0xb0000
	v_lshl_add_u64 v[216:217], s[18:19], 0, v[136:137]
	s_addc_u32 s69, s19, 0
	s_add_i32 s70, s44, s29
	global_load_lds_dwordx4 v[216:217], off
	v_lshl_add_u64 v[218:219], s[68:69], 0, v[132:133]
	s_mov_b32 m0, s70
	v_lshl_add_u64 v[220:221], s[20:21], 0, v[134:135]
	global_load_lds_dwordx4 v[218:219], off
	v_lshl_add_u64 v[218:219], s[68:69], 0, v[136:137]
	s_add_i32 m0, s70, 0x2000
	s_nop 0
	global_load_lds_dwordx4 v[218:219], off
	v_lshl_add_u64 v[218:219], s[20:21], 0, v[130:131]
	s_mov_b32 m0, s30
	s_nop 0
	global_load_lds_dwordx4 v[218:219], off
	s_mov_b32 m0, s31
	s_nop 0
	global_load_lds_dwordx4 v[220:221], off
	s_waitcnt vmcnt(8)
	s_waitcnt lgkmcnt(0)
	s_barrier
	s_waitcnt lgkmcnt(0)
	v_mfma_f32_16x16x32_bf16 v[62:65], v[144:147], v[182:185], v[62:65]
	v_mfma_f32_16x16x32_bf16 v[58:61], v[158:161], v[182:185], v[58:61]
	v_mfma_f32_16x16x32_bf16 v[54:57], v[144:147], v[190:193], v[54:57]
	v_mfma_f32_16x16x32_bf16 v[46:49], v[158:161], v[190:193], v[46:49]
	v_mfma_f32_16x16x32_bf16 v[38:41], v[144:147], v[198:201], v[38:41]
	v_mfma_f32_16x16x32_bf16 v[30:33], v[158:161], v[198:201], v[30:33]
	v_mfma_f32_16x16x32_bf16 v[22:25], v[144:147], v[206:209], v[22:25]
	v_mfma_f32_16x16x32_bf16 v[14:17], v[158:161], v[206:209], v[14:17]
	v_mfma_f32_16x16x32_bf16 v[62:65], v[154:157], v[186:189], v[62:65]
	v_mfma_f32_16x16x32_bf16 v[58:61], v[162:165], v[186:189], v[58:61]
	v_mfma_f32_16x16x32_bf16 v[54:57], v[154:157], v[194:197], v[54:57]
	v_mfma_f32_16x16x32_bf16 v[46:49], v[162:165], v[194:197], v[46:49]
	v_mfma_f32_16x16x32_bf16 v[38:41], v[154:157], v[202:205], v[38:41]
	v_mfma_f32_16x16x32_bf16 v[30:33], v[162:165], v[202:205], v[30:33]
	v_mfma_f32_16x16x32_bf16 v[22:25], v[154:157], v[210:213], v[22:25]
	v_mfma_f32_16x16x32_bf16 v[14:17], v[162:165], v[210:213], v[14:17]
	v_mfma_f32_16x16x32_bf16 v[50:53], v[166:169], v[182:185], v[50:53]
	v_mfma_f32_16x16x32_bf16 v[42:45], v[174:177], v[182:185], v[42:45]
	v_mfma_f32_16x16x32_bf16 v[34:37], v[166:169], v[190:193], v[34:37]
	v_mfma_f32_16x16x32_bf16 v[26:29], v[174:177], v[190:193], v[26:29]
	v_mfma_f32_16x16x32_bf16 v[18:21], v[166:169], v[198:201], v[18:21]
	v_mfma_f32_16x16x32_bf16 v[10:13], v[174:177], v[198:201], v[10:13]
	v_mfma_f32_16x16x32_bf16 v[6:9], v[166:169], v[206:209], v[6:9]
	v_mfma_f32_16x16x32_bf16 v[2:5], v[174:177], v[206:209], v[2:5]
	v_mfma_f32_16x16x32_bf16 v[50:53], v[170:173], v[186:189], v[50:53]
	v_mfma_f32_16x16x32_bf16 v[42:45], v[178:181], v[186:189], v[42:45]
	v_mfma_f32_16x16x32_bf16 v[34:37], v[170:173], v[194:197], v[34:37]
	v_mfma_f32_16x16x32_bf16 v[26:29], v[178:181], v[194:197], v[26:29]
	v_mfma_f32_16x16x32_bf16 v[18:21], v[170:173], v[202:205], v[18:21]
	v_mfma_f32_16x16x32_bf16 v[10:13], v[178:181], v[202:205], v[10:13]
	v_mfma_f32_16x16x32_bf16 v[6:9], v[170:173], v[210:213], v[6:9]
	v_mfma_f32_16x16x32_bf16 v[2:5], v[178:181], v[210:213], v[2:5]
	s_barrier
	s_add_i32 s68, 0, 0x18000
	v_add_u32_e32 v153, s68, v148
	s_add_i32 s69, 0, 0x1c000
	ds_read_b128 v[144:147], v153
	ds_read_b128 v[154:157], v153 offset:1024
	ds_read_b128 v[158:161], v153 offset:2048
	ds_read_b128 v[162:165], v153 offset:3072
	v_add_u32_e32 v153, s69, v148
	ds_read_b128 v[166:169], v153
	ds_read_b128 v[170:173], v153 offset:1024
	ds_read_b128 v[174:177], v153 offset:2048
	ds_read_b128 v[178:181], v153 offset:3072
	s_add_u32 s20, s20, 0xb0000
	s_addc_u32 s21, s21, 0
	s_mov_b32 m0, s34
	v_lshl_add_u64 v[222:223], s[20:21], 0, v[130:131]
	ds_read_b128 v[182:185], v152 offset:32768
	ds_read_b128 v[186:189], v152 offset:33792
	ds_read_b128 v[190:193], v152 offset:34816
	ds_read_b128 v[194:197], v152 offset:35840
	ds_read_b128 v[198:201], v152 offset:36864
	ds_read_b128 v[202:205], v152 offset:37888
	ds_read_b128 v[206:209], v152 offset:38912
	ds_read_b128 v[210:213], v152 offset:39936
	global_load_lds_dwordx4 v[222:223], off
	v_lshl_add_u64 v[222:223], s[20:21], 0, v[134:135]
	s_mov_b32 m0, s35
	s_nop 0
	global_load_lds_dwordx4 v[222:223], off
	s_waitcnt vmcnt(8)
	s_waitcnt lgkmcnt(0)
	s_barrier
	s_waitcnt lgkmcnt(0)
	v_mfma_f32_16x16x32_bf16 v[126:129], v[144:147], v[182:185], v[126:129]
	v_mfma_f32_16x16x32_bf16 v[122:125], v[158:161], v[182:185], v[122:125]
	v_mfma_f32_16x16x32_bf16 v[118:121], v[144:147], v[190:193], v[118:121]
	v_mfma_f32_16x16x32_bf16 v[110:113], v[158:161], v[190:193], v[110:113]
	v_mfma_f32_16x16x32_bf16 v[102:105], v[144:147], v[198:201], v[102:105]
	v_mfma_f32_16x16x32_bf16 v[94:97], v[158:161], v[198:201], v[94:97]
	v_mfma_f32_16x16x32_bf16 v[86:89], v[144:147], v[206:209], v[86:89]
	v_mfma_f32_16x16x32_bf16 v[78:81], v[158:161], v[206:209], v[78:81]
	v_mfma_f32_16x16x32_bf16 v[126:129], v[154:157], v[186:189], v[126:129]
	v_mfma_f32_16x16x32_bf16 v[122:125], v[162:165], v[186:189], v[122:125]
	v_mfma_f32_16x16x32_bf16 v[118:121], v[154:157], v[194:197], v[118:121]
	v_mfma_f32_16x16x32_bf16 v[110:113], v[162:165], v[194:197], v[110:113]
	v_mfma_f32_16x16x32_bf16 v[102:105], v[154:157], v[202:205], v[102:105]
	v_mfma_f32_16x16x32_bf16 v[94:97], v[162:165], v[202:205], v[94:97]
	v_mfma_f32_16x16x32_bf16 v[86:89], v[154:157], v[210:213], v[86:89]
	v_mfma_f32_16x16x32_bf16 v[78:81], v[162:165], v[210:213], v[78:81]
	v_mfma_f32_16x16x32_bf16 v[114:117], v[166:169], v[182:185], v[114:117]
	v_mfma_f32_16x16x32_bf16 v[106:109], v[174:177], v[182:185], v[106:109]
	v_mfma_f32_16x16x32_bf16 v[98:101], v[166:169], v[190:193], v[98:101]
	v_mfma_f32_16x16x32_bf16 v[90:93], v[174:177], v[190:193], v[90:93]
	v_mfma_f32_16x16x32_bf16 v[82:85], v[166:169], v[198:201], v[82:85]
	v_mfma_f32_16x16x32_bf16 v[74:77], v[174:177], v[198:201], v[74:77]
	v_mfma_f32_16x16x32_bf16 v[70:73], v[166:169], v[206:209], v[70:73]
	v_mfma_f32_16x16x32_bf16 v[66:69], v[174:177], v[206:209], v[66:69]
	v_mfma_f32_16x16x32_bf16 v[114:117], v[170:173], v[186:189], v[114:117]
	v_mfma_f32_16x16x32_bf16 v[106:109], v[178:181], v[186:189], v[106:109]
	v_mfma_f32_16x16x32_bf16 v[98:101], v[170:173], v[194:197], v[98:101]
	v_mfma_f32_16x16x32_bf16 v[90:93], v[178:181], v[194:197], v[90:93]
	v_mfma_f32_16x16x32_bf16 v[82:85], v[170:173], v[202:205], v[82:85]
	v_mfma_f32_16x16x32_bf16 v[74:77], v[178:181], v[202:205], v[74:77]
	v_mfma_f32_16x16x32_bf16 v[70:73], v[170:173], v[210:213], v[70:73]
	v_mfma_f32_16x16x32_bf16 v[66:69], v[178:181], v[210:213], v[66:69]
	s_barrier
	s_add_i32 s20, s68, s29
	v_lshl_add_u64 v[214:215], v[214:215], 0, s[6:7]
	s_mov_b32 m0, s20
	ds_read_b128 v[182:185], v152 offset:49152
	ds_read_b128 v[186:189], v152 offset:50176
	ds_read_b128 v[190:193], v152 offset:51200
	ds_read_b128 v[194:197], v152 offset:52224
	ds_read_b128 v[198:201], v152 offset:53248
	ds_read_b128 v[202:205], v152 offset:54272
	ds_read_b128 v[206:209], v152 offset:55296
	ds_read_b128 v[210:213], v152 offset:56320
	global_load_lds_dwordx4 v[214:215], off
	s_add_i32 m0, s20, 0x2000
	s_add_u32 s18, s18, 0xb0080
	v_lshl_add_u64 v[214:215], v[216:217], 0, s[6:7]
	s_addc_u32 s19, s19, 0
	s_add_i32 s20, s69, s29
	global_load_lds_dwordx4 v[214:215], off
	v_lshl_add_u64 v[214:215], s[18:19], 0, v[132:133]
	s_mov_b32 m0, s20
	s_nop 0
	global_load_lds_dwordx4 v[214:215], off
	v_lshl_add_u64 v[214:215], s[18:19], 0, v[136:137]
	s_add_i32 m0, s20, 0x2000
	s_nop 0
	global_load_lds_dwordx4 v[214:215], off
	v_lshl_add_u64 v[214:215], v[218:219], 0, s[6:7]
	s_mov_b32 m0, s39
	s_nop 0
	global_load_lds_dwordx4 v[214:215], off
	v_lshl_add_u64 v[214:215], v[220:221], 0, s[6:7]
	s_mov_b32 m0, s40
	s_nop 0
	global_load_lds_dwordx4 v[214:215], off
	s_waitcnt vmcnt(8)
	s_waitcnt lgkmcnt(0)
	s_barrier
	s_waitcnt lgkmcnt(0)
	v_mfma_f32_16x16x32_bf16 v[62:65], v[144:147], v[182:185], v[62:65]
	v_mfma_f32_16x16x32_bf16 v[58:61], v[158:161], v[182:185], v[58:61]
	v_mfma_f32_16x16x32_bf16 v[54:57], v[144:147], v[190:193], v[54:57]
	v_mfma_f32_16x16x32_bf16 v[46:49], v[158:161], v[190:193], v[46:49]
	v_mfma_f32_16x16x32_bf16 v[38:41], v[144:147], v[198:201], v[38:41]
	v_mfma_f32_16x16x32_bf16 v[30:33], v[158:161], v[198:201], v[30:33]
	v_mfma_f32_16x16x32_bf16 v[22:25], v[144:147], v[206:209], v[22:25]
	v_mfma_f32_16x16x32_bf16 v[14:17], v[158:161], v[206:209], v[14:17]
	v_mfma_f32_16x16x32_bf16 v[62:65], v[154:157], v[186:189], v[62:65]
	v_mfma_f32_16x16x32_bf16 v[58:61], v[162:165], v[186:189], v[58:61]
	v_mfma_f32_16x16x32_bf16 v[54:57], v[154:157], v[194:197], v[54:57]
	v_mfma_f32_16x16x32_bf16 v[46:49], v[162:165], v[194:197], v[46:49]
	v_mfma_f32_16x16x32_bf16 v[38:41], v[154:157], v[202:205], v[38:41]
	v_mfma_f32_16x16x32_bf16 v[30:33], v[162:165], v[202:205], v[30:33]
	v_mfma_f32_16x16x32_bf16 v[22:25], v[154:157], v[210:213], v[22:25]
	v_mfma_f32_16x16x32_bf16 v[14:17], v[162:165], v[210:213], v[14:17]
	v_mfma_f32_16x16x32_bf16 v[50:53], v[166:169], v[182:185], v[50:53]
	v_mfma_f32_16x16x32_bf16 v[42:45], v[174:177], v[182:185], v[42:45]
	v_mfma_f32_16x16x32_bf16 v[34:37], v[166:169], v[190:193], v[34:37]
	v_mfma_f32_16x16x32_bf16 v[26:29], v[174:177], v[190:193], v[26:29]
	v_mfma_f32_16x16x32_bf16 v[18:21], v[166:169], v[198:201], v[18:21]
	v_mfma_f32_16x16x32_bf16 v[10:13], v[174:177], v[198:201], v[10:13]
	v_mfma_f32_16x16x32_bf16 v[6:9], v[166:169], v[206:209], v[6:9]
	v_mfma_f32_16x16x32_bf16 v[2:5], v[174:177], v[206:209], v[2:5]
	v_mfma_f32_16x16x32_bf16 v[50:53], v[170:173], v[186:189], v[50:53]
	v_mfma_f32_16x16x32_bf16 v[42:45], v[178:181], v[186:189], v[42:45]
	v_mfma_f32_16x16x32_bf16 v[34:37], v[170:173], v[194:197], v[34:37]
	v_mfma_f32_16x16x32_bf16 v[26:29], v[178:181], v[194:197], v[26:29]
	v_mfma_f32_16x16x32_bf16 v[18:21], v[170:173], v[202:205], v[18:21]
	v_mfma_f32_16x16x32_bf16 v[10:13], v[178:181], v[202:205], v[10:13]
	v_mfma_f32_16x16x32_bf16 v[6:9], v[170:173], v[210:213], v[6:9]
	v_mfma_f32_16x16x32_bf16 v[2:5], v[178:181], v[210:213], v[2:5]
	s_barrier
	s_add_i32 s18, s65, 2
	s_add_u32 s16, s16, 0x100
	s_addc_u32 s17, s17, 0
	s_add_u32 s11, s11, 0x100
	s_addc_u32 s64, s64, 0
	s_cmp_ge_i32 s65, s51
	s_mov_b32 s65, s18
	s_cbranch_scc0 .LBB0_221
	s_and_b64 vcc, exec, s[8:9]
	s_cbranch_vccz .LBB0_224
	s_barrier

.LBB0_286:
	s_setprio 0
	s_cmp_lt_i32 s90, 4
	s_cselect_b64 s[0:1], -1, 0
	s_cmp_gt_i32 s91, 3
	s_cselect_b64 s[2:3], -1, 0
	s_and_b64 s[0:1], s[0:1], s[2:3]
	s_andn2_b64 vcc, exec, s[0:1]
	s_cbranch_vccnz .LBB0_382
	s_lshl_b32 s0, s82, 3
	s_add_i32 s0, s0, s83
	s_cmpk_gt_i32 s0, 0x41ff
	v_mbcnt_lo_u32_b32 v82, -1, 0
	v_mbcnt_hi_u32_b32 v82, -1, v82
	s_cbranch_scc1 .LBB0_327
	s_waitcnt lgkmcnt(0)
	s_mov_b32 s4, s0
	v_mbcnt_lo_u32_b32 v1, -1, 0
	v_mbcnt_hi_u32_b32 v1, -1, v1
	v_lshlrev_b32_e32 v19, 4, v1
	v_lshlrev_b32_e32 v1, 3, v1
	s_add_u32 s14, s66, 0x1000
	s_addc_u32 s15, s67, 0
	global_load_dwordx4 v[2:5], v19, s[14:15] offset:0
	global_load_dwordx4 v[6:9], v19, s[14:15] offset:1024
	global_load_dwordx4 v[10:13], v19, s[14:15] offset:2048
	global_load_dwordx4 v[14:17], v19, s[14:15] offset:3072
	s_add_u32 s14, s66, 0x2000
	s_addc_u32 s15, s67, 0
	global_load_dwordx4 v[20:23], v19, s[14:15] offset:0
	global_load_dwordx4 v[24:27], v19, s[14:15] offset:1024
	global_load_dwordx4 v[28:31], v19, s[14:15] offset:2048
	global_load_dwordx4 v[32:35], v19, s[14:15] offset:3072
	s_mov_b32 s34, 0xffff0000
	s_mov_b32 s35, 0xf800000
	v_mov_b32_e32 v69, 0x358637bd
	v_mov_b32_e32 v80, 0x260
	s_lshl_b32 s23, s33, 3
	s_lshl_b32 s20, s33, 14
	s_lshl_b32 s21, s33, 15
	s_mul_i32 s22, s23, 3
	s_sub_i32 s22, 0x4000, s22
	s_mov_b32 s5, s4
	s_lshl_b32 s36, s4, 11
	s_lshl_b32 s37, s4, 12
	s_add_u32 s6, s26, 0xae00000
	s_addc_u32 s7, s27, 0
	s_add_u32 s6, s6, s36
	s_addc_u32 s7, s7, 0
	s_add_u32 s8, s52, s37
	s_addc_u32 s9, s53, 0
	s_add_u32 s10, s26, 0xf000000
	s_addc_u32 s11, s27, 0
	s_add_u32 s10, s10, s36
	s_addc_u32 s11, s11, 0
	s_add_u32 s12, s26, 0x3000000
	s_addc_u32 s13, s27, 0
	s_add_u32 s12, s12, s36
	s_addc_u32 s13, s13, 0

.LBB0_382:
	s_cmp_lt_i32 s90, 5
	s_cselect_b64 s[0:1], -1, 0
	s_cmp_gt_i32 s91, 4
	s_cselect_b64 s[2:3], -1, 0
	s_and_b64 s[0:1], s[0:1], s[2:3]
	s_andn2_b64 vcc, exec, s[0:1]
	s_cbranch_vccnz .LBB0_850
	s_cmpk_lt_u32 s80, 0x100
	s_cbranch_scc1 .Lprio_skip_2
	s_setprio 1

.LBB0_398:
	ds_read_b128 v[130:133], v167
	ds_read_b128 v[152:155], v167 offset:1024
	ds_read_b128 v[156:159], v167 offset:2048
	ds_read_b128 v[160:163], v167 offset:3072
	ds_read_b128 v[172:175], v168
	ds_read_b128 v[176:179], v168 offset:1024
	ds_read_b128 v[180:183], v168 offset:2048
	ds_read_b128 v[184:187], v168 offset:3072
	s_add_u32 s50, s86, 0xfffc0080
	s_addc_u32 s51, s87, -1
	s_cmp_eq_u32 s49, 12
	s_cselect_b32 s91, s7, s51
	s_cselect_b32 s90, s23, s50
	s_cselect_b32 s89, s35, s48
	s_cselect_b32 s88, s46, s47
	v_lshl_add_u64 v[220:221], s[86:87], 0, v[144:145]
	s_add_i32 m0, s75, 0xc000
	ds_read_b128 v[188:191], v169
	ds_read_b128 v[192:195], v169 offset:1024
	ds_read_b128 v[196:199], v169 offset:2048
	ds_read_b128 v[200:203], v169 offset:3072
	ds_read_b128 v[204:207], v169 offset:4096
	ds_read_b128 v[208:211], v169 offset:5120
	ds_read_b128 v[212:215], v169 offset:6144
	ds_read_b128 v[216:219], v169 offset:7168
	global_load_lds_dwordx4 v[220:221], off
	v_lshl_add_u64 v[220:221], s[86:87], 0, v[146:147]
	s_add_i32 m0, s75, 0xe000
	s_nop 0
	global_load_lds_dwordx4 v[220:221], off
	s_waitcnt vmcnt(8)
	s_waitcnt lgkmcnt(0)
	s_barrier
	s_waitcnt lgkmcnt(0)
	v_mfma_f32_16x16x32_bf16 v[126:129], v[130:133], v[188:191], v[126:129]
	v_mfma_f32_16x16x32_bf16 v[122:125], v[156:159], v[188:191], v[122:125]
	v_mfma_f32_16x16x32_bf16 v[110:113], v[130:133], v[196:199], v[110:113]
	v_mfma_f32_16x16x32_bf16 v[106:109], v[156:159], v[196:199], v[106:109]
	v_mfma_f32_16x16x32_bf16 v[94:97], v[130:133], v[204:207], v[94:97]
	v_mfma_f32_16x16x32_bf16 v[90:93], v[156:159], v[204:207], v[90:93]
	v_mfma_f32_16x16x32_bf16 v[78:81], v[130:133], v[212:215], v[78:81]
	v_mfma_f32_16x16x32_bf16 v[74:77], v[156:159], v[212:215], v[74:77]
	v_mfma_f32_16x16x32_bf16 v[126:129], v[152:155], v[192:195], v[126:129]
	v_mfma_f32_16x16x32_bf16 v[122:125], v[160:163], v[192:195], v[122:125]
	v_mfma_f32_16x16x32_bf16 v[110:113], v[152:155], v[200:203], v[110:113]
	v_mfma_f32_16x16x32_bf16 v[106:109], v[160:163], v[200:203], v[106:109]
	v_mfma_f32_16x16x32_bf16 v[94:97], v[152:155], v[208:211], v[94:97]
	v_mfma_f32_16x16x32_bf16 v[90:93], v[160:163], v[208:211], v[90:93]
	v_mfma_f32_16x16x32_bf16 v[78:81], v[152:155], v[216:219], v[78:81]
	v_mfma_f32_16x16x32_bf16 v[74:77], v[160:163], v[216:219], v[74:77]
	v_mfma_f32_16x16x32_bf16 v[118:121], v[172:175], v[188:191], v[118:121]
	v_mfma_f32_16x16x32_bf16 v[114:117], v[180:183], v[188:191], v[114:117]
	v_mfma_f32_16x16x32_bf16 v[102:105], v[172:175], v[196:199], v[102:105]
	v_mfma_f32_16x16x32_bf16 v[98:101], v[180:183], v[196:199], v[98:101]
	v_mfma_f32_16x16x32_bf16 v[86:89], v[172:175], v[204:207], v[86:89]
	v_mfma_f32_16x16x32_bf16 v[82:85], v[180:183], v[204:207], v[82:85]
	v_mfma_f32_16x16x32_bf16 v[70:73], v[172:175], v[212:215], v[70:73]
	v_mfma_f32_16x16x32_bf16 v[66:69], v[180:183], v[212:215], v[66:69]
	v_mfma_f32_16x16x32_bf16 v[118:121], v[176:179], v[192:195], v[118:121]
	v_mfma_f32_16x16x32_bf16 v[114:117], v[184:187], v[192:195], v[114:117]
	v_mfma_f32_16x16x32_bf16 v[102:105], v[176:179], v[200:203], v[102:105]
	v_mfma_f32_16x16x32_bf16 v[98:101], v[184:187], v[200:203], v[98:101]
	v_mfma_f32_16x16x32_bf16 v[86:89], v[176:179], v[208:211], v[86:89]
	v_mfma_f32_16x16x32_bf16 v[82:85], v[184:187], v[208:211], v[82:85]
	v_mfma_f32_16x16x32_bf16 v[70:73], v[176:179], v[216:219], v[70:73]
	v_mfma_f32_16x16x32_bf16 v[66:69], v[184:187], v[216:219], v[66:69]
	s_barrier
	s_add_i32 s50, s68, s74
	v_lshl_add_u64 v[220:221], s[88:89], 0, v[136:137]
	s_mov_b32 m0, s50
	ds_read_b128 v[188:191], v169 offset:16384
	ds_read_b128 v[192:195], v169 offset:17408
	ds_read_b128 v[196:199], v169 offset:18432
	ds_read_b128 v[200:203], v169 offset:19456
	ds_read_b128 v[204:207], v169 offset:20480
	ds_read_b128 v[208:211], v169 offset:21504
	ds_read_b128 v[212:215], v169 offset:22528
	ds_read_b128 v[216:219], v169 offset:23552
	global_load_lds_dwordx4 v[220:221], off
	s_add_i32 m0, s50, 0x2000
	s_add_u32 s50, s88, 0x40000
	v_lshl_add_u64 v[222:223], s[88:89], 0, v[140:141]
	s_addc_u32 s51, s89, 0
	s_add_i32 s85, s28, s74
	global_load_lds_dwordx4 v[222:223], off
	v_lshl_add_u64 v[224:225], s[50:51], 0, v[136:137]
	s_mov_b32 m0, s85
	v_lshl_add_u64 v[226:227], s[90:91], 0, v[138:139]
	global_load_lds_dwordx4 v[224:225], off
	v_lshl_add_u64 v[224:225], s[50:51], 0, v[140:141]
	s_add_i32 m0, s85, 0x2000
	s_nop 0
	global_load_lds_dwordx4 v[224:225], off
	v_lshl_add_u64 v[224:225], s[90:91], 0, v[134:135]
	s_mov_b32 m0, s75
	s_nop 0
	global_load_lds_dwordx4 v[224:225], off
	s_mov_b32 m0, s76
	s_nop 0
	global_load_lds_dwordx4 v[226:227], off
	s_waitcnt vmcnt(8)
	s_waitcnt lgkmcnt(0)
	s_barrier
	s_waitcnt lgkmcnt(0)
	v_mfma_f32_16x16x32_bf16 v[62:65], v[130:133], v[188:191], v[62:65]
	v_mfma_f32_16x16x32_bf16 v[58:61], v[156:159], v[188:191], v[58:61]
	v_mfma_f32_16x16x32_bf16 v[46:49], v[130:133], v[196:199], v[46:49]
	v_mfma_f32_16x16x32_bf16 v[42:45], v[156:159], v[196:199], v[42:45]
	v_mfma_f32_16x16x32_bf16 v[30:33], v[130:133], v[204:207], v[30:33]
	v_mfma_f32_16x16x32_bf16 v[26:29], v[156:159], v[204:207], v[26:29]
	v_mfma_f32_16x16x32_bf16 v[14:17], v[130:133], v[212:215], v[14:17]
	v_mfma_f32_16x16x32_bf16 v[10:13], v[156:159], v[212:215], v[10:13]
	v_mfma_f32_16x16x32_bf16 v[62:65], v[152:155], v[192:195], v[62:65]
	v_mfma_f32_16x16x32_bf16 v[58:61], v[160:163], v[192:195], v[58:61]
	v_mfma_f32_16x16x32_bf16 v[46:49], v[152:155], v[200:203], v[46:49]
	v_mfma_f32_16x16x32_bf16 v[42:45], v[160:163], v[200:203], v[42:45]
	v_mfma_f32_16x16x32_bf16 v[30:33], v[152:155], v[208:211], v[30:33]
	v_mfma_f32_16x16x32_bf16 v[26:29], v[160:163], v[208:211], v[26:29]
	v_mfma_f32_16x16x32_bf16 v[14:17], v[152:155], v[216:219], v[14:17]
	v_mfma_f32_16x16x32_bf16 v[10:13], v[160:163], v[216:219], v[10:13]
	v_mfma_f32_16x16x32_bf16 v[54:57], v[172:175], v[188:191], v[54:57]
	v_mfma_f32_16x16x32_bf16 v[50:53], v[180:183], v[188:191], v[50:53]
	v_mfma_f32_16x16x32_bf16 v[38:41], v[172:175], v[196:199], v[38:41]
	v_mfma_f32_16x16x32_bf16 v[34:37], v[180:183], v[196:199], v[34:37]
	v_mfma_f32_16x16x32_bf16 v[22:25], v[172:175], v[204:207], v[22:25]
	v_mfma_f32_16x16x32_bf16 v[18:21], v[180:183], v[204:207], v[18:21]
	v_mfma_f32_16x16x32_bf16 v[6:9], v[172:175], v[212:215], v[6:9]
	v_mfma_f32_16x16x32_bf16 v[2:5], v[180:183], v[212:215], v[2:5]
	v_mfma_f32_16x16x32_bf16 v[54:57], v[176:179], v[192:195], v[54:57]
	v_mfma_f32_16x16x32_bf16 v[50:53], v[184:187], v[192:195], v[50:53]
	v_mfma_f32_16x16x32_bf16 v[38:41], v[176:179], v[200:203], v[38:41]
	v_mfma_f32_16x16x32_bf16 v[34:37], v[184:187], v[200:203], v[34:37]
	v_mfma_f32_16x16x32_bf16 v[22:25], v[176:179], v[208:211], v[22:25]
	v_mfma_f32_16x16x32_bf16 v[18:21], v[184:187], v[208:211], v[18:21]
	v_mfma_f32_16x16x32_bf16 v[6:9], v[176:179], v[216:219], v[6:9]
	v_mfma_f32_16x16x32_bf16 v[2:5], v[184:187], v[216:219], v[2:5]
	s_barrier
	s_add_i32 s85, 0, 0x18000
	v_add_u32_e32 v142, s85, v165
	s_add_i32 s92, 0, 0x1c000
	ds_read_b128 v[130:133], v142
	ds_read_b128 v[152:155], v142 offset:1024
	ds_read_b128 v[156:159], v142 offset:2048
	ds_read_b128 v[160:163], v142 offset:3072
	v_add_u32_e32 v142, s92, v165
	ds_read_b128 v[172:175], v142
	ds_read_b128 v[176:179], v142 offset:1024
	ds_read_b128 v[180:183], v142 offset:2048
	ds_read_b128 v[184:187], v142 offset:3072
	s_add_u32 s50, s90, 0x40000
	s_addc_u32 s51, s91, 0
	s_mov_b32 m0, s77
	v_lshl_add_u64 v[228:229], s[50:51], 0, v[134:135]
	ds_read_b128 v[188:191], v169 offset:32768
	ds_read_b128 v[192:195], v169 offset:33792
	ds_read_b128 v[196:199], v169 offset:34816
	ds_read_b128 v[200:203], v169 offset:35840
	ds_read_b128 v[204:207], v169 offset:36864
	ds_read_b128 v[208:211], v169 offset:37888
	ds_read_b128 v[212:215], v169 offset:38912
	ds_read_b128 v[216:219], v169 offset:39936
	global_load_lds_dwordx4 v[228:229], off
	v_lshl_add_u64 v[228:229], s[50:51], 0, v[138:139]
	s_mov_b32 m0, s78
	s_nop 0
	global_load_lds_dwordx4 v[228:229], off
	s_waitcnt vmcnt(8)
	s_waitcnt lgkmcnt(0)
	s_barrier
	s_waitcnt lgkmcnt(0)
	v_mfma_f32_16x16x32_bf16 v[126:129], v[130:133], v[188:191], v[126:129]
	v_mfma_f32_16x16x32_bf16 v[122:125], v[156:159], v[188:191], v[122:125]
	v_mfma_f32_16x16x32_bf16 v[110:113], v[130:133], v[196:199], v[110:113]
	v_mfma_f32_16x16x32_bf16 v[106:109], v[156:159], v[196:199], v[106:109]
	v_mfma_f32_16x16x32_bf16 v[94:97], v[130:133], v[204:207], v[94:97]
	v_mfma_f32_16x16x32_bf16 v[90:93], v[156:159], v[204:207], v[90:93]
	v_mfma_f32_16x16x32_bf16 v[78:81], v[130:133], v[212:215], v[78:81]
	v_mfma_f32_16x16x32_bf16 v[74:77], v[156:159], v[212:215], v[74:77]
	v_mfma_f32_16x16x32_bf16 v[126:129], v[152:155], v[192:195], v[126:129]
	v_mfma_f32_16x16x32_bf16 v[122:125], v[160:163], v[192:195], v[122:125]
	v_mfma_f32_16x16x32_bf16 v[110:113], v[152:155], v[200:203], v[110:113]
	v_mfma_f32_16x16x32_bf16 v[106:109], v[160:163], v[200:203], v[106:109]
	v_mfma_f32_16x16x32_bf16 v[94:97], v[152:155], v[208:211], v[94:97]
	v_mfma_f32_16x16x32_bf16 v[90:93], v[160:163], v[208:211], v[90:93]
	v_mfma_f32_16x16x32_bf16 v[78:81], v[152:155], v[216:219], v[78:81]
	v_mfma_f32_16x16x32_bf16 v[74:77], v[160:163], v[216:219], v[74:77]
	v_mfma_f32_16x16x32_bf16 v[118:121], v[172:175], v[188:191], v[118:121]
	v_mfma_f32_16x16x32_bf16 v[114:117], v[180:183], v[188:191], v[114:117]
	v_mfma_f32_16x16x32_bf16 v[102:105], v[172:175], v[196:199], v[102:105]
	v_mfma_f32_16x16x32_bf16 v[98:101], v[180:183], v[196:199], v[98:101]
	v_mfma_f32_16x16x32_bf16 v[86:89], v[172:175], v[204:207], v[86:89]
	v_mfma_f32_16x16x32_bf16 v[82:85], v[180:183], v[204:207], v[82:85]
	v_mfma_f32_16x16x32_bf16 v[70:73], v[172:175], v[212:215], v[70:73]
	v_mfma_f32_16x16x32_bf16 v[66:69], v[180:183], v[212:215], v[66:69]
	v_mfma_f32_16x16x32_bf16 v[118:121], v[176:179], v[192:195], v[118:121]
	v_mfma_f32_16x16x32_bf16 v[114:117], v[184:187], v[192:195], v[114:117]
	v_mfma_f32_16x16x32_bf16 v[102:105], v[176:179], v[200:203], v[102:105]
	v_mfma_f32_16x16x32_bf16 v[98:101], v[184:187], v[200:203], v[98:101]
	v_mfma_f32_16x16x32_bf16 v[86:89], v[176:179], v[208:211], v[86:89]
	v_mfma_f32_16x16x32_bf16 v[82:85], v[184:187], v[208:211], v[82:85]
	v_mfma_f32_16x16x32_bf16 v[70:73], v[176:179], v[216:219], v[70:73]
	v_mfma_f32_16x16x32_bf16 v[66:69], v[184:187], v[216:219], v[66:69]
	s_barrier
	s_add_i32 s50, s85, s74
	v_lshl_add_u64 v[220:221], v[220:221], 0, s[38:39]
	s_mov_b32 m0, s50
	ds_read_b128 v[188:191], v169 offset:49152
	ds_read_b128 v[192:195], v169 offset:50176
	ds_read_b128 v[196:199], v169 offset:51200
	ds_read_b128 v[200:203], v169 offset:52224
	ds_read_b128 v[204:207], v169 offset:53248
	ds_read_b128 v[208:211], v169 offset:54272
	ds_read_b128 v[212:215], v169 offset:55296
	ds_read_b128 v[216:219], v169 offset:56320
	global_load_lds_dwordx4 v[220:221], off
	s_add_i32 m0, s50, 0x2000
	s_add_u32 s50, s88, 0x40080
	v_lshl_add_u64 v[220:221], v[222:223], 0, s[38:39]
	s_addc_u32 s51, s89, 0
	s_add_i32 s85, s92, s74
	global_load_lds_dwordx4 v[220:221], off
	v_lshl_add_u64 v[220:221], s[50:51], 0, v[136:137]
	s_mov_b32 m0, s85
	s_nop 0
	global_load_lds_dwordx4 v[220:221], off
	v_lshl_add_u64 v[220:221], s[50:51], 0, v[140:141]
	s_add_i32 m0, s85, 0x2000
	s_nop 0
	global_load_lds_dwordx4 v[220:221], off
	v_lshl_add_u64 v[220:221], v[224:225], 0, s[38:39]
	s_mov_b32 m0, s25
	s_nop 0
	global_load_lds_dwordx4 v[220:221], off
	v_lshl_add_u64 v[220:221], v[226:227], 0, s[38:39]
	s_mov_b32 m0, s69
	s_nop 0
	global_load_lds_dwordx4 v[220:221], off
	s_waitcnt vmcnt(8)
	s_waitcnt lgkmcnt(0)
	s_barrier
	s_waitcnt lgkmcnt(0)
	v_mfma_f32_16x16x32_bf16 v[62:65], v[130:133], v[188:191], v[62:65]
	v_mfma_f32_16x16x32_bf16 v[58:61], v[156:159], v[188:191], v[58:61]
	v_mfma_f32_16x16x32_bf16 v[46:49], v[130:133], v[196:199], v[46:49]
	v_mfma_f32_16x16x32_bf16 v[42:45], v[156:159], v[196:199], v[42:45]
	v_mfma_f32_16x16x32_bf16 v[30:33], v[130:133], v[204:207], v[30:33]
	v_mfma_f32_16x16x32_bf16 v[26:29], v[156:159], v[204:207], v[26:29]
	v_mfma_f32_16x16x32_bf16 v[14:17], v[130:133], v[212:215], v[14:17]
	v_mfma_f32_16x16x32_bf16 v[10:13], v[156:159], v[212:215], v[10:13]
	v_mfma_f32_16x16x32_bf16 v[62:65], v[152:155], v[192:195], v[62:65]
	v_mfma_f32_16x16x32_bf16 v[58:61], v[160:163], v[192:195], v[58:61]
	v_mfma_f32_16x16x32_bf16 v[46:49], v[152:155], v[200:203], v[46:49]
	v_mfma_f32_16x16x32_bf16 v[42:45], v[160:163], v[200:203], v[42:45]
	v_mfma_f32_16x16x32_bf16 v[30:33], v[152:155], v[208:211], v[30:33]
	v_mfma_f32_16x16x32_bf16 v[26:29], v[160:163], v[208:211], v[26:29]
	v_mfma_f32_16x16x32_bf16 v[14:17], v[152:155], v[216:219], v[14:17]
	v_mfma_f32_16x16x32_bf16 v[10:13], v[160:163], v[216:219], v[10:13]
	v_mfma_f32_16x16x32_bf16 v[54:57], v[172:175], v[188:191], v[54:57]
	v_mfma_f32_16x16x32_bf16 v[50:53], v[180:183], v[188:191], v[50:53]
	v_mfma_f32_16x16x32_bf16 v[38:41], v[172:175], v[196:199], v[38:41]
	v_mfma_f32_16x16x32_bf16 v[34:37], v[180:183], v[196:199], v[34:37]
	v_mfma_f32_16x16x32_bf16 v[22:25], v[172:175], v[204:207], v[22:25]
	v_mfma_f32_16x16x32_bf16 v[18:21], v[180:183], v[204:207], v[18:21]
	v_mfma_f32_16x16x32_bf16 v[6:9], v[172:175], v[212:215], v[6:9]
	v_mfma_f32_16x16x32_bf16 v[2:5], v[180:183], v[212:215], v[2:5]
	v_mfma_f32_16x16x32_bf16 v[54:57], v[176:179], v[192:195], v[54:57]
	v_mfma_f32_16x16x32_bf16 v[50:53], v[184:187], v[192:195], v[50:53]
	v_mfma_f32_16x16x32_bf16 v[38:41], v[176:179], v[200:203], v[38:41]
	v_mfma_f32_16x16x32_bf16 v[34:37], v[184:187], v[200:203], v[34:37]
	v_mfma_f32_16x16x32_bf16 v[22:25], v[176:179], v[208:211], v[22:25]
	v_mfma_f32_16x16x32_bf16 v[18:21], v[184:187], v[208:211], v[18:21]
	v_mfma_f32_16x16x32_bf16 v[6:9], v[176:179], v[216:219], v[6:9]
	v_mfma_f32_16x16x32_bf16 v[2:5], v[184:187], v[216:219], v[2:5]
	s_barrier
	s_add_i32 s49, s49, 2
	s_add_u32 s86, s86, 0x100
	s_addc_u32 s87, s87, 0
	s_add_u32 s47, s47, 0x100
	s_addc_u32 s48, s48, 0
	s_cmp_gt_u32 s49, 13
	s_cbranch_scc0 .LBB0_398
	s_and_b64 vcc, exec, s[44:45]
	s_cbranch_vccz .LBB0_401
	s_barrier

.LBB0_850:
	s_setprio 0
	s_cmp_lt_i32 s90, 6
	s_cselect_b64 s[0:1], -1, 0
	s_cmp_gt_i32 s91, 5
	s_cselect_b64 s[2:3], -1, 0
	s_and_b64 s[36:37], s[0:1], s[2:3]
	v_cndmask_b32_e64 v1, 0, 1, s[36:37]
	v_cmp_ne_u32_e64 s[78:79], 1, v1
	s_andn2_b64 vcc, exec, s[36:37]
	s_cbranch_vccnz .LBB0_971
	s_and_b32 s22, s80, 0xffffffc0
	v_mbcnt_lo_u32_b32 v26, -1, 0
	v_mbcnt_hi_u32_b32 v26, -1, v26
	s_movk_i32 s0, 0x1000
	v_add_u32_e32 v10, s22, v26
	v_cmp_gt_i32_e32 vcc, s0, v10
	s_and_saveexec_b64 s[30:31], vcc
	s_cbranch_execz .LBB0_889
	v_and_b32_e32 v1, 0x1ff, v10
	v_readlane_b32 s4, v255, 23
	v_lshlrev_b32_e32 v18, 2, v1
	v_readlane_b32 s5, v255, 24
	v_readlane_b32 s6, v255, 25
	v_readlane_b32 s7, v255, 26
	v_readlane_b32 s8, v255, 27
	v_readlane_b32 s9, v255, 28
	v_readlane_b32 s10, v255, 29
	v_readlane_b32 s11, v255, 30
	v_readlane_b32 s12, v255, 31
	v_readlane_b32 s13, v255, 32
	v_readlane_b32 s14, v255, 33
	v_readlane_b32 s15, v255, 34
	v_max_i32_e32 v1, 0xe00, v10
	v_readlane_b32 s16, v255, 35
	v_readlane_b32 s17, v255, 36
	v_readlane_b32 s18, v255, 37
	v_readlane_b32 s19, v255, 38
	s_mov_b64 s[4:5], s[8:9]
	v_readlane_b32 s40, v255, 7
	v_sub_u32_e32 v1, v1, v10
	s_movk_i32 s0, 0x1ff
	v_mov_b32_e32 v19, 0
	s_mov_b64 s[6:7], s[10:11]
	s_mov_b64 s[8:9], s[12:13]
	v_readlane_b32 s48, v255, 15
	v_readlane_b32 s49, v255, 16
	v_readlane_b32 s50, v255, 17
	v_readlane_b32 s51, v255, 18
	v_readlane_b32 s54, v255, 21
	v_readlane_b32 s55, v255, 22
	v_add_u32_e32 v1, 0x1ff, v1
	s_waitcnt lgkmcnt(0)
	v_lshl_add_u64 v[2:3], s[6:7], 0, v[18:19]
	v_lshl_add_u64 v[4:5], s[4:5], 0, v[18:19]
	v_lshl_add_u64 v[6:7], s[54:55], 0, v[18:19]
	v_lshl_add_u64 v[8:9], s[50:51], 0, v[18:19]
	v_lshl_add_u64 v[12:13], s[8:9], 0, v[18:19]
	v_lshl_add_u64 v[14:15], s[48:49], 0, v[18:19]
	v_cmp_lt_u32_e32 vcc, s0, v1
	s_mov_b64 s[0:1], -1
	v_mov_b32_e32 v16, v10
	s_mov_b64 s[10:11], s[14:15]
	s_mov_b64 s[12:13], s[16:17]
	s_mov_b64 s[14:15], s[18:19]
	v_readlane_b32 s41, v255, 8
	v_readlane_b32 s42, v255, 9
	v_readlane_b32 s43, v255, 10
	v_readlane_b32 s44, v255, 11
	v_readlane_b32 s45, v255, 12
	v_readlane_b32 s46, v255, 13
	v_readlane_b32 s47, v255, 14
	v_readlane_b32 s52, v255, 19
	v_readlane_b32 s53, v255, 20
	s_and_saveexec_b64 s[34:35], vcc
	s_cbranch_execz .LBB0_860
	v_lshrrev_b32_e32 v1, 9, v1
	v_add_u32_e32 v11, 0x200, v10
	v_add_u32_e32 v20, -1, v1
	v_cmp_lt_u32_e32 vcc, 1, v20
	v_mov_b64_e32 v[16:17], v[10:11]
	s_and_saveexec_b64 s[38:39], vcc
	s_cbranch_execz .LBB0_857
	v_lshrrev_b32_e32 v16, 1, v20
	s_lshl_b32 s0, s83, 8
	v_add_u32_e32 v16, 1, v16
	s_add_i32 s0, s0, 0
	v_and_b32_e32 v21, -2, v16
	v_lshl_add_u32 v16, v26, 2, s0
	v_readlane_b32 s0, v255, 7
	v_readlane_b32 s8, v255, 15
	v_readlane_b32 s9, v255, 16
	s_mov_b32 s23, 0
	v_add_u32_e32 v22, 0x4240, v16
	s_mov_b64 s[40:41], 0
	s_movk_i32 s25, 0x1ff
	v_mov_b32_e32 v19, 0
	v_mov_b64_e32 v[16:17], v[10:11]
	v_readlane_b32 s1, v255, 8
	v_readlane_b32 s2, v255, 9
	v_readlane_b32 s3, v255, 10
	v_readlane_b32 s4, v255, 11
	v_readlane_b32 s5, v255, 12
	v_readlane_b32 s6, v255, 13
	v_readlane_b32 s7, v255, 14
	s_mov_b64 s[52:53], s[8:9]
	v_readlane_b32 s10, v255, 17
	v_readlane_b32 s11, v255, 18
	v_readlane_b32 s12, v255, 19
	v_readlane_b32 s13, v255, 20
	v_readlane_b32 s14, v255, 21
	v_readlane_b32 s15, v255, 22
	s_mov_b64 s[50:51], s[6:7]
	s_mov_b64 s[48:49], s[4:5]
	s_mov_b64 s[46:47], s[2:3]
	s_mov_b64 s[44:45], s[0:1]

.LBB0_1494:
	s_cmp_lt_i32 s90, 9
	s_cselect_b64 s[0:1], -1, 0
	s_cmp_gt_i32 s91, 8
	s_cselect_b64 s[2:3], -1, 0
	s_and_b64 s[0:1], s[0:1], s[2:3]
	s_andn2_b64 vcc, exec, s[0:1]
	s_cbranch_vccnz .LBB0_1590
	s_cmpk_lt_u32 s80, 0x100
	s_cbranch_scc1 .Lprio_skip_3
	s_setprio 1
.Lprio_skip_3:
	s_cmpk_gt_i32 s24, 0xff
	v_readfirstlane_b32 s8, v0
	v_mbcnt_lo_u32_b32 v1, -1, 0
	v_mbcnt_hi_u32_b32 v1, -1, v1
	s_cbranch_scc0 .LBB0_1501
	s_and_b32 s0, s24, 0x7fffffe0
	s_mov_b64 s[2:3], 0
	s_cmpk_eq_i32 s0, 0x100
	s_mov_b64 s[0:1], 0
	s_cbranch_scc0 .LBB0_1498
	s_bfe_u32 s4, s24, 0x30002
	v_sub_co_u32_e64 v1, s[0:1], s4, 4
	s_and_b64 s[0:1], s[0:1], exec
	v_readfirstlane_b32 s0, v1
	s_cselect_b32 s18, s4, s0
	s_cmp_gt_u32 s4, 3
	s_cselect_b32 s20, 0x41, 64
	s_lshl_b32 s0, s24, 2
	s_and_b32 s77, s0, 12
	s_mov_b64 s[0:1], -1
	s_mov_b32 s78, 4
	s_and_b64 vcc, exec, s[2:3]
	s_cbranch_vccz .LBB0_1502
	s_branch .LBB0_1499

.LBB0_1522:
	ds_read_b128 v[144:147], v150
	ds_read_b128 v[154:157], v150 offset:1024
	ds_read_b128 v[158:161], v150 offset:2048
	ds_read_b128 v[162:165], v150 offset:3072
	ds_read_b128 v[166:169], v151
	ds_read_b128 v[170:173], v151 offset:1024
	ds_read_b128 v[174:177], v151 offset:2048
	ds_read_b128 v[178:181], v151 offset:3072
	s_add_u32 s19, s34, 0xfffc0080
	s_addc_u32 s36, s35, -1
	s_cmp_eq_u32 s78, s17
	s_cselect_b32 s39, s23, s36
	s_cselect_b32 s38, s22, s19
	s_cselect_b32 s37, s31, s15
	s_cselect_b32 s36, s30, s13
	v_lshl_add_u64 v[214:215], s[34:35], 0, v[138:139]
	s_add_i32 m0, s21, 0xc000
	ds_read_b128 v[182:185], v152
	ds_read_b128 v[186:189], v152 offset:1024
	ds_read_b128 v[190:193], v152 offset:2048
	ds_read_b128 v[194:197], v152 offset:3072
	ds_read_b128 v[198:201], v152 offset:4096
	ds_read_b128 v[202:205], v152 offset:5120
	ds_read_b128 v[206:209], v152 offset:6144
	ds_read_b128 v[210:213], v152 offset:7168
	global_load_lds_dwordx4 v[214:215], off
	v_lshl_add_u64 v[214:215], s[34:35], 0, v[140:141]
	s_add_i32 m0, s21, 0xe000
	s_nop 0
	global_load_lds_dwordx4 v[214:215], off
	s_waitcnt vmcnt(8)
	s_waitcnt lgkmcnt(0)
	s_barrier
	s_waitcnt lgkmcnt(0)
	v_mfma_f32_16x16x32_bf16 v[126:129], v[144:147], v[182:185], v[126:129]
	v_mfma_f32_16x16x32_bf16 v[122:125], v[158:161], v[182:185], v[122:125]
	v_mfma_f32_16x16x32_bf16 v[118:121], v[144:147], v[190:193], v[118:121]
	v_mfma_f32_16x16x32_bf16 v[110:113], v[158:161], v[190:193], v[110:113]
	v_mfma_f32_16x16x32_bf16 v[102:105], v[144:147], v[198:201], v[102:105]
	v_mfma_f32_16x16x32_bf16 v[94:97], v[158:161], v[198:201], v[94:97]
	v_mfma_f32_16x16x32_bf16 v[86:89], v[144:147], v[206:209], v[86:89]
	v_mfma_f32_16x16x32_bf16 v[78:81], v[158:161], v[206:209], v[78:81]
	v_mfma_f32_16x16x32_bf16 v[126:129], v[154:157], v[186:189], v[126:129]
	v_mfma_f32_16x16x32_bf16 v[122:125], v[162:165], v[186:189], v[122:125]
	v_mfma_f32_16x16x32_bf16 v[118:121], v[154:157], v[194:197], v[118:121]
	v_mfma_f32_16x16x32_bf16 v[110:113], v[162:165], v[194:197], v[110:113]
	v_mfma_f32_16x16x32_bf16 v[102:105], v[154:157], v[202:205], v[102:105]
	v_mfma_f32_16x16x32_bf16 v[94:97], v[162:165], v[202:205], v[94:97]
	v_mfma_f32_16x16x32_bf16 v[86:89], v[154:157], v[210:213], v[86:89]
	v_mfma_f32_16x16x32_bf16 v[78:81], v[162:165], v[210:213], v[78:81]
	v_mfma_f32_16x16x32_bf16 v[114:117], v[166:169], v[182:185], v[114:117]
	v_mfma_f32_16x16x32_bf16 v[106:109], v[174:177], v[182:185], v[106:109]
	v_mfma_f32_16x16x32_bf16 v[98:101], v[166:169], v[190:193], v[98:101]
	v_mfma_f32_16x16x32_bf16 v[90:93], v[174:177], v[190:193], v[90:93]
	v_mfma_f32_16x16x32_bf16 v[82:85], v[166:169], v[198:201], v[82:85]
	v_mfma_f32_16x16x32_bf16 v[74:77], v[174:177], v[198:201], v[74:77]
	v_mfma_f32_16x16x32_bf16 v[70:73], v[166:169], v[206:209], v[70:73]
	v_mfma_f32_16x16x32_bf16 v[66:69], v[174:177], v[206:209], v[66:69]
	v_mfma_f32_16x16x32_bf16 v[114:117], v[170:173], v[186:189], v[114:117]
	v_mfma_f32_16x16x32_bf16 v[106:109], v[178:181], v[186:189], v[106:109]
	v_mfma_f32_16x16x32_bf16 v[98:101], v[170:173], v[194:197], v[98:101]
	v_mfma_f32_16x16x32_bf16 v[90:93], v[178:181], v[194:197], v[90:93]
	v_mfma_f32_16x16x32_bf16 v[82:85], v[170:173], v[202:205], v[82:85]
	v_mfma_f32_16x16x32_bf16 v[74:77], v[178:181], v[202:205], v[74:77]
	v_mfma_f32_16x16x32_bf16 v[70:73], v[170:173], v[210:213], v[70:73]
	v_mfma_f32_16x16x32_bf16 v[66:69], v[178:181], v[210:213], v[66:69]
	s_barrier
	s_add_i32 s19, s55, s41
	v_lshl_add_u64 v[214:215], s[36:37], 0, v[132:133]
	s_mov_b32 m0, s19
	ds_read_b128 v[182:185], v152 offset:16384
	ds_read_b128 v[186:189], v152 offset:17408
	ds_read_b128 v[190:193], v152 offset:18432
	ds_read_b128 v[194:197], v152 offset:19456
	ds_read_b128 v[198:201], v152 offset:20480
	ds_read_b128 v[202:205], v152 offset:21504
	ds_read_b128 v[206:209], v152 offset:22528
	ds_read_b128 v[210:213], v152 offset:23552
	global_load_lds_dwordx4 v[214:215], off
	s_add_i32 m0, s19, 0x2000
	s_add_u32 s80, s36, 0x40000
	v_lshl_add_u64 v[216:217], s[36:37], 0, v[136:137]
	s_addc_u32 s81, s37, 0
	s_add_i32 s19, s56, s41
	global_load_lds_dwordx4 v[216:217], off
	v_lshl_add_u64 v[218:219], s[80:81], 0, v[132:133]
	s_mov_b32 m0, s19
	v_lshl_add_u64 v[220:221], s[38:39], 0, v[134:135]
	global_load_lds_dwordx4 v[218:219], off
	v_lshl_add_u64 v[218:219], s[80:81], 0, v[136:137]
	s_add_i32 m0, s19, 0x2000
	s_nop 0
	global_load_lds_dwordx4 v[218:219], off
	v_lshl_add_u64 v[218:219], s[38:39], 0, v[130:131]
	s_mov_b32 m0, s21
	s_nop 0
	global_load_lds_dwordx4 v[218:219], off
	s_mov_b32 m0, s42
	s_nop 0
	global_load_lds_dwordx4 v[220:221], off
	s_waitcnt vmcnt(8)
	s_waitcnt lgkmcnt(0)
	s_barrier
	s_waitcnt lgkmcnt(0)
	v_mfma_f32_16x16x32_bf16 v[62:65], v[144:147], v[182:185], v[62:65]
	v_mfma_f32_16x16x32_bf16 v[58:61], v[158:161], v[182:185], v[58:61]
	v_mfma_f32_16x16x32_bf16 v[54:57], v[144:147], v[190:193], v[54:57]
	v_mfma_f32_16x16x32_bf16 v[46:49], v[158:161], v[190:193], v[46:49]
	v_mfma_f32_16x16x32_bf16 v[38:41], v[144:147], v[198:201], v[38:41]
	v_mfma_f32_16x16x32_bf16 v[30:33], v[158:161], v[198:201], v[30:33]
	v_mfma_f32_16x16x32_bf16 v[22:25], v[144:147], v[206:209], v[22:25]
	v_mfma_f32_16x16x32_bf16 v[14:17], v[158:161], v[206:209], v[14:17]
	v_mfma_f32_16x16x32_bf16 v[62:65], v[154:157], v[186:189], v[62:65]
	v_mfma_f32_16x16x32_bf16 v[58:61], v[162:165], v[186:189], v[58:61]
	v_mfma_f32_16x16x32_bf16 v[54:57], v[154:157], v[194:197], v[54:57]
	v_mfma_f32_16x16x32_bf16 v[46:49], v[162:165], v[194:197], v[46:49]
	v_mfma_f32_16x16x32_bf16 v[38:41], v[154:157], v[202:205], v[38:41]
	v_mfma_f32_16x16x32_bf16 v[30:33], v[162:165], v[202:205], v[30:33]
	v_mfma_f32_16x16x32_bf16 v[22:25], v[154:157], v[210:213], v[22:25]
	v_mfma_f32_16x16x32_bf16 v[14:17], v[162:165], v[210:213], v[14:17]
	v_mfma_f32_16x16x32_bf16 v[50:53], v[166:169], v[182:185], v[50:53]
	v_mfma_f32_16x16x32_bf16 v[42:45], v[174:177], v[182:185], v[42:45]
	v_mfma_f32_16x16x32_bf16 v[34:37], v[166:169], v[190:193], v[34:37]
	v_mfma_f32_16x16x32_bf16 v[26:29], v[174:177], v[190:193], v[26:29]
	v_mfma_f32_16x16x32_bf16 v[18:21], v[166:169], v[198:201], v[18:21]
	v_mfma_f32_16x16x32_bf16 v[10:13], v[174:177], v[198:201], v[10:13]
	v_mfma_f32_16x16x32_bf16 v[6:9], v[166:169], v[206:209], v[6:9]
	v_mfma_f32_16x16x32_bf16 v[2:5], v[174:177], v[206:209], v[2:5]
	v_mfma_f32_16x16x32_bf16 v[50:53], v[170:173], v[186:189], v[50:53]
	v_mfma_f32_16x16x32_bf16 v[42:45], v[178:181], v[186:189], v[42:45]
	v_mfma_f32_16x16x32_bf16 v[34:37], v[170:173], v[194:197], v[34:37]
	v_mfma_f32_16x16x32_bf16 v[26:29], v[178:181], v[194:197], v[26:29]
	v_mfma_f32_16x16x32_bf16 v[18:21], v[170:173], v[202:205], v[18:21]
	v_mfma_f32_16x16x32_bf16 v[10:13], v[178:181], v[202:205], v[10:13]
	v_mfma_f32_16x16x32_bf16 v[6:9], v[170:173], v[210:213], v[6:9]
	v_mfma_f32_16x16x32_bf16 v[2:5], v[178:181], v[210:213], v[2:5]
	s_barrier
	s_add_i32 s19, 0, 0x18000
	v_add_u32_e32 v153, s19, v148
	s_add_i32 s79, 0, 0x1c000
	ds_read_b128 v[144:147], v153
	ds_read_b128 v[154:157], v153 offset:1024
	ds_read_b128 v[158:161], v153 offset:2048
	ds_read_b128 v[162:165], v153 offset:3072
	v_add_u32_e32 v153, s79, v148
	ds_read_b128 v[166:169], v153
	ds_read_b128 v[170:173], v153 offset:1024
	ds_read_b128 v[174:177], v153 offset:2048
	ds_read_b128 v[178:181], v153 offset:3072
	s_add_u32 s38, s38, 0x40000
	s_addc_u32 s39, s39, 0
	s_mov_b32 m0, s43
	v_lshl_add_u64 v[222:223], s[38:39], 0, v[130:131]
	ds_read_b128 v[182:185], v152 offset:32768
	ds_read_b128 v[186:189], v152 offset:33792
	ds_read_b128 v[190:193], v152 offset:34816
	ds_read_b128 v[194:197], v152 offset:35840
	ds_read_b128 v[198:201], v152 offset:36864
	ds_read_b128 v[202:205], v152 offset:37888
	ds_read_b128 v[206:209], v152 offset:38912
	ds_read_b128 v[210:213], v152 offset:39936
	global_load_lds_dwordx4 v[222:223], off
	v_lshl_add_u64 v[222:223], s[38:39], 0, v[134:135]
	s_mov_b32 m0, s44
	s_nop 0
	global_load_lds_dwordx4 v[222:223], off
	s_waitcnt vmcnt(8)
	s_waitcnt lgkmcnt(0)
	s_barrier
	s_waitcnt lgkmcnt(0)
	v_mfma_f32_16x16x32_bf16 v[126:129], v[144:147], v[182:185], v[126:129]
	v_mfma_f32_16x16x32_bf16 v[122:125], v[158:161], v[182:185], v[122:125]
	v_mfma_f32_16x16x32_bf16 v[118:121], v[144:147], v[190:193], v[118:121]
	v_mfma_f32_16x16x32_bf16 v[110:113], v[158:161], v[190:193], v[110:113]
	v_mfma_f32_16x16x32_bf16 v[102:105], v[144:147], v[198:201], v[102:105]
	v_mfma_f32_16x16x32_bf16 v[94:97], v[158:161], v[198:201], v[94:97]
	v_mfma_f32_16x16x32_bf16 v[86:89], v[144:147], v[206:209], v[86:89]
	v_mfma_f32_16x16x32_bf16 v[78:81], v[158:161], v[206:209], v[78:81]
	v_mfma_f32_16x16x32_bf16 v[126:129], v[154:157], v[186:189], v[126:129]
	v_mfma_f32_16x16x32_bf16 v[122:125], v[162:165], v[186:189], v[122:125]
	v_mfma_f32_16x16x32_bf16 v[118:121], v[154:157], v[194:197], v[118:121]
	v_mfma_f32_16x16x32_bf16 v[110:113], v[162:165], v[194:197], v[110:113]
	v_mfma_f32_16x16x32_bf16 v[102:105], v[154:157], v[202:205], v[102:105]
	v_mfma_f32_16x16x32_bf16 v[94:97], v[162:165], v[202:205], v[94:97]
	v_mfma_f32_16x16x32_bf16 v[86:89], v[154:157], v[210:213], v[86:89]
	v_mfma_f32_16x16x32_bf16 v[78:81], v[162:165], v[210:213], v[78:81]
	v_mfma_f32_16x16x32_bf16 v[114:117], v[166:169], v[182:185], v[114:117]
	v_mfma_f32_16x16x32_bf16 v[106:109], v[174:177], v[182:185], v[106:109]
	v_mfma_f32_16x16x32_bf16 v[98:101], v[166:169], v[190:193], v[98:101]
	v_mfma_f32_16x16x32_bf16 v[90:93], v[174:177], v[190:193], v[90:93]
	v_mfma_f32_16x16x32_bf16 v[82:85], v[166:169], v[198:201], v[82:85]
	v_mfma_f32_16x16x32_bf16 v[74:77], v[174:177], v[198:201], v[74:77]
	v_mfma_f32_16x16x32_bf16 v[70:73], v[166:169], v[206:209], v[70:73]
	v_mfma_f32_16x16x32_bf16 v[66:69], v[174:177], v[206:209], v[66:69]
	v_mfma_f32_16x16x32_bf16 v[114:117], v[170:173], v[186:189], v[114:117]
	v_mfma_f32_16x16x32_bf16 v[106:109], v[178:181], v[186:189], v[106:109]
	v_mfma_f32_16x16x32_bf16 v[98:101], v[170:173], v[194:197], v[98:101]
	v_mfma_f32_16x16x32_bf16 v[90:93], v[178:181], v[194:197], v[90:93]
	v_mfma_f32_16x16x32_bf16 v[82:85], v[170:173], v[202:205], v[82:85]
	v_mfma_f32_16x16x32_bf16 v[74:77], v[178:181], v[202:205], v[74:77]
	v_mfma_f32_16x16x32_bf16 v[70:73], v[170:173], v[210:213], v[70:73]
	v_mfma_f32_16x16x32_bf16 v[66:69], v[178:181], v[210:213], v[66:69]
	s_barrier
	s_add_i32 s19, s19, s41
	v_lshl_add_u64 v[214:215], v[214:215], 0, s[6:7]
	s_mov_b32 m0, s19
	ds_read_b128 v[182:185], v152 offset:49152
	ds_read_b128 v[186:189], v152 offset:50176
	ds_read_b128 v[190:193], v152 offset:51200
	ds_read_b128 v[194:197], v152 offset:52224
	ds_read_b128 v[198:201], v152 offset:53248
	ds_read_b128 v[202:205], v152 offset:54272
	ds_read_b128 v[206:209], v152 offset:55296
	ds_read_b128 v[210:213], v152 offset:56320
	global_load_lds_dwordx4 v[214:215], off
	s_add_i32 m0, s19, 0x2000
	s_add_u32 s36, s36, 0x40080
	v_lshl_add_u64 v[214:215], v[216:217], 0, s[6:7]
	s_addc_u32 s37, s37, 0
	s_add_i32 s19, s79, s41
	global_load_lds_dwordx4 v[214:215], off
	v_lshl_add_u64 v[214:215], s[36:37], 0, v[132:133]
	s_mov_b32 m0, s19
	s_nop 0
	global_load_lds_dwordx4 v[214:215], off
	v_lshl_add_u64 v[214:215], s[36:37], 0, v[136:137]
	s_add_i32 m0, s19, 0x2000
	s_nop 0
	global_load_lds_dwordx4 v[214:215], off
	v_lshl_add_u64 v[214:215], v[218:219], 0, s[6:7]
	s_mov_b32 m0, s49
	s_nop 0
	global_load_lds_dwordx4 v[214:215], off
	v_lshl_add_u64 v[214:215], v[220:221], 0, s[6:7]
	s_mov_b32 m0, s50
	s_nop 0
	global_load_lds_dwordx4 v[214:215], off
	s_waitcnt vmcnt(8)
	s_waitcnt lgkmcnt(0)
	s_barrier
	s_waitcnt lgkmcnt(0)
	v_mfma_f32_16x16x32_bf16 v[62:65], v[144:147], v[182:185], v[62:65]
	v_mfma_f32_16x16x32_bf16 v[58:61], v[158:161], v[182:185], v[58:61]
	v_mfma_f32_16x16x32_bf16 v[54:57], v[144:147], v[190:193], v[54:57]
	v_mfma_f32_16x16x32_bf16 v[46:49], v[158:161], v[190:193], v[46:49]
	v_mfma_f32_16x16x32_bf16 v[38:41], v[144:147], v[198:201], v[38:41]
	v_mfma_f32_16x16x32_bf16 v[30:33], v[158:161], v[198:201], v[30:33]
	v_mfma_f32_16x16x32_bf16 v[22:25], v[144:147], v[206:209], v[22:25]
	v_mfma_f32_16x16x32_bf16 v[14:17], v[158:161], v[206:209], v[14:17]
	v_mfma_f32_16x16x32_bf16 v[62:65], v[154:157], v[186:189], v[62:65]
	v_mfma_f32_16x16x32_bf16 v[58:61], v[162:165], v[186:189], v[58:61]
	v_mfma_f32_16x16x32_bf16 v[54:57], v[154:157], v[194:197], v[54:57]
	v_mfma_f32_16x16x32_bf16 v[46:49], v[162:165], v[194:197], v[46:49]
	v_mfma_f32_16x16x32_bf16 v[38:41], v[154:157], v[202:205], v[38:41]
	v_mfma_f32_16x16x32_bf16 v[30:33], v[162:165], v[202:205], v[30:33]
	v_mfma_f32_16x16x32_bf16 v[22:25], v[154:157], v[210:213], v[22:25]
	v_mfma_f32_16x16x32_bf16 v[14:17], v[162:165], v[210:213], v[14:17]
	v_mfma_f32_16x16x32_bf16 v[50:53], v[166:169], v[182:185], v[50:53]
	v_mfma_f32_16x16x32_bf16 v[42:45], v[174:177], v[182:185], v[42:45]
	v_mfma_f32_16x16x32_bf16 v[34:37], v[166:169], v[190:193], v[34:37]
	v_mfma_f32_16x16x32_bf16 v[26:29], v[174:177], v[190:193], v[26:29]
	v_mfma_f32_16x16x32_bf16 v[18:21], v[166:169], v[198:201], v[18:21]
	v_mfma_f32_16x16x32_bf16 v[10:13], v[174:177], v[198:201], v[10:13]
	v_mfma_f32_16x16x32_bf16 v[6:9], v[166:169], v[206:209], v[6:9]
	v_mfma_f32_16x16x32_bf16 v[2:5], v[174:177], v[206:209], v[2:5]
	v_mfma_f32_16x16x32_bf16 v[50:53], v[170:173], v[186:189], v[50:53]
	v_mfma_f32_16x16x32_bf16 v[42:45], v[178:181], v[186:189], v[42:45]
	v_mfma_f32_16x16x32_bf16 v[34:37], v[170:173], v[194:197], v[34:37]
	v_mfma_f32_16x16x32_bf16 v[26:29], v[178:181], v[194:197], v[26:29]
	v_mfma_f32_16x16x32_bf16 v[18:21], v[170:173], v[202:205], v[18:21]
	v_mfma_f32_16x16x32_bf16 v[10:13], v[178:181], v[202:205], v[10:13]
	v_mfma_f32_16x16x32_bf16 v[6:9], v[170:173], v[210:213], v[6:9]
	v_mfma_f32_16x16x32_bf16 v[2:5], v[178:181], v[210:213], v[2:5]
	s_barrier
	s_add_i32 s19, s17, 2
	s_add_u32 s34, s34, 0x100
	s_addc_u32 s35, s35, 0
	s_add_u32 s13, s13, 0x100
	s_addc_u32 s15, s15, 0
	s_cmp_ge_i32 s17, s78
	s_mov_b32 s17, s19
	s_cbranch_scc0 .LBB0_1522
	s_and_b64 vcc, exec, s[8:9]
	s_cbranch_vccz .LBB0_1525
	s_barrier

.LBB0_1590:
	s_setprio 0
	s_cmp_lt_i32 s90, 10
	s_cselect_b64 s[0:1], -1, 0
	s_cmp_gt_i32 s91, 9
	s_cselect_b64 s[2:3], -1, 0
	s_and_b64 s[0:1], s[0:1], s[2:3]
	s_andn2_b64 vcc, exec, s[0:1]
	s_cbranch_vccnz .LBB0_1685
	s_lshl_b32 s0, s82, 3
	s_add_i32 s0, s0, s83
	s_cmpk_gt_i32 s0, 0x41ff
	s_waitcnt vmcnt(0)
	v_mbcnt_lo_u32_b32 v18, -1, 0
	v_mbcnt_hi_u32_b32 v18, -1, v18
	s_cbranch_scc1 .LBB0_1631
	s_waitcnt lgkmcnt(0)
	s_mov_b32 s4, s0
	v_mbcnt_lo_u32_b32 v1, -1, 0
	v_mbcnt_hi_u32_b32 v1, -1, v1
	v_lshlrev_b32_e32 v19, 4, v1
	v_lshlrev_b32_e32 v1, 3, v1
	s_add_u32 s14, s66, 0x3000
	s_addc_u32 s15, s67, 0
	global_load_dwordx4 v[2:5], v19, s[14:15] offset:0
	global_load_dwordx4 v[6:9], v19, s[14:15] offset:1024
	global_load_dwordx4 v[10:13], v19, s[14:15] offset:2048
	global_load_dwordx4 v[14:17], v19, s[14:15] offset:3072
	s_add_u32 s14, s66, 0x4000
	s_addc_u32 s15, s67, 0
	global_load_dwordx4 v[20:23], v19, s[14:15] offset:0
	global_load_dwordx4 v[24:27], v19, s[14:15] offset:1024
	global_load_dwordx4 v[28:31], v19, s[14:15] offset:2048
	global_load_dwordx4 v[32:35], v19, s[14:15] offset:3072
	s_mov_b32 s34, 0xffff0000
	s_mov_b32 s35, 0xf800000
	v_mov_b32_e32 v69, 0x358637bd
	v_mov_b32_e32 v80, 0x260
	s_lshl_b32 s23, s33, 3
	s_lshl_b32 s20, s33, 14
	s_lshl_b32 s21, s33, 15
	s_mul_i32 s22, s23, 3
	s_sub_i32 s22, 0x4000, s22
	s_mov_b32 s5, s4
	s_lshl_b32 s36, s4, 11
	s_lshl_b32 s37, s4, 12
	s_add_u32 s6, s26, 0xae00000
	s_addc_u32 s7, s27, 0
	s_add_u32 s6, s6, s36
	s_addc_u32 s7, s7, 0
	s_add_u32 s8, s26, 0xf000000
	s_addc_u32 s9, s27, 0
	s_add_u32 s8, s8, s36
	s_addc_u32 s9, s9, 0
	s_add_u32 s10, s26, 0xf000000
	s_addc_u32 s11, s27, 0
	s_add_u32 s10, s10, s36
	s_addc_u32 s11, s11, 0
	s_add_u32 s12, s26, 0x3000000
	s_addc_u32 s13, s27, 0
	s_add_u32 s12, s12, s36
	s_addc_u32 s13, s13, 0

.LBB0_1685:
	s_cmp_lt_i32 s90, 11
	s_cselect_b64 s[0:1], -1, 0
	s_cmp_gt_i32 s91, 10
	s_cselect_b64 s[2:3], -1, 0
	s_and_b64 s[0:1], s[0:1], s[2:3]
	s_andn2_b64 vcc, exec, s[0:1]
	s_cbranch_vccnz .LBB0_1760
	s_cmpk_lt_u32 s80, 0x100
	s_cbranch_scc1 .Lprio_skip_4
	s_setprio 1
.Lprio_skip_4:
	s_cmpk_lt_i32 s24, 0x5ac
	v_readfirstlane_b32 s3, v0
	v_mbcnt_lo_u32_b32 v1, -1, 0
	v_mbcnt_hi_u32_b32 v1, -1, v1
	s_cbranch_scc0 .LBB0_1706
	s_waitcnt lgkmcnt(0)
	v_lshrrev_b32_e32 v3, 1, v0
	v_and_b32_e32 v13, 24, v3
	v_lshrrev_b32_e32 v3, 5, v0
	s_add_u32 s25, s26, 0x3000000
	v_lshlrev_b32_e32 v1, 4, v0
	v_and_b32_e32 v2, 32, v0
	v_and_b32_e32 v3, 4, v3
	v_bfe_u32 v4, v0, 2, 2
	s_addc_u32 s28, s27, 0
	v_bfe_u32 v12, v0, 2, 4
	v_bitop3_b32 v10, v1, v2, 48 bitop3:0x6c
	v_and_b32_e32 v11, 64, v0
	v_or3_b32 v3, v3, v4, v13
	v_lshrrev_b32_e32 v4, 3, v0
	v_or_b32_e32 v14, 0x2000, v1
	s_add_u32 s29, s26, 0x1400000
	v_or_b32_e32 v2, v10, v11
	v_and_or_b32 v5, v4, 48, v12
	v_and_or_b32 v4, v4, 32, v3
	v_lshrrev_b32_e32 v1, 7, v14
	s_movk_i32 s0, 0x70
	s_addc_u32 s34, s27, 0
	v_lshl_or_b32 v132, v4, 11, v2
	v_and_or_b32 v4, v1, s0, v12
	s_movk_i32 s0, 0x60
	s_ashr_i32 s36, s24, 31
	v_and_or_b32 v1, v1, s0, v3
	s_lshr_b32 s0, s36, 29
	s_add_i32 s0, s24, s0
	s_and_b32 s1, s0, -8
	s_sub_i32 s1, s24, s1
	s_lshr_b32 s6, s3, 6
	s_mul_i32 s4, s1, 0xb5
	s_lshr_b32 s8, s3, 8
	s_lshl_b32 s35, s6, 10
	s_add_i32 s4, s4, 4
	s_ashr_i32 s0, s0, 3
	s_mul_i32 s2, s1, 0xb6
	s_cmp_lt_i32 s1, 4
	s_cselect_b32 s1, s2, s4
	s_add_i32 s1, s1, s0
	s_mul_hi_i32 s0, s1, 0x2e8ba2e9
	s_lshr_b32 s2, s0, 31
	s_ashr_i32 s0, s0, 5
	s_add_i32 s0, s0, s2
	s_lshl_b32 s4, s0, 3
	s_sub_i32 s2, 0x42, s4
	s_mulk_i32 s0, 0xb0
	s_min_u32 s5, s2, 8
	s_sub_i32 s7, s1, s0
	v_lshl_or_b32 v134, v4, 11, v2
	s_sext_i32_i16 s0, s7
	v_cvt_f32_ubyte0_e32 v4, s5
	v_lshl_or_b32 v130, v5, 11, v2
	v_cvt_f32_i32_e32 v3, s0
	v_rcp_iflag_f32_e32 v5, v4
	v_lshl_or_b32 v136, v1, 11, v2
	s_ashr_i32 s0, s0, 30
	s_or_b32 s2, s0, 1
	v_mul_f32_e32 v1, v3, v5
	v_trunc_f32_e32 v1, v1
	v_fma_f32 v2, -v1, v4, v3
	v_cvt_i32_f32_e32 v1, v1
	v_cmp_ge_f32_e64 s[0:1], |v2|, v4
	s_and_b64 s[0:1], s[0:1], exec
	s_cselect_b32 s0, s2, 0
	v_readfirstlane_b32 s1, v1
	s_add_i32 s2, s1, s0
	s_mul_i32 s0, s2, s5
	s_sub_i32 s0, s7, s0
	s_sext_i32_i16 s0, s0
	s_add_i32 s18, s4, s0
	s_ashr_i32 s19, s18, 31
	s_bfe_i64 s[4:5], s[2:3], 0x100000
	s_lshl_b64 s[0:1], s[18:19], 19
	s_lshl_b64 s[4:5], s[4:5], 19
	s_add_u32 s22, s29, s4
	s_addc_u32 s23, s34, s5
	s_add_i32 s19, s35, 0
	s_add_i32 m0, s19, 0x10000
	v_mov_b32_e32 v133, 0
	global_load_lds_dwordx4 v132, s[22:23]
	s_add_i32 m0, s19, 0x12000
	s_add_u32 s4, s22, 0x40000
	global_load_lds_dwordx4 v136, s[22:23]
	s_addc_u32 s5, s23, 0
	s_add_i32 m0, s19, 0x14000
	v_mov_b32_e32 v137, v133
	global_load_lds_dwordx4 v132, s[4:5]
	s_add_i32 m0, s19, 0x16000
	s_add_u32 s20, s25, s0
	s_addc_u32 s21, s28, s1
	s_add_i32 s37, s19, 0x2000
	global_load_lds_dwordx4 v136, s[4:5]
	s_mov_b32 m0, s19
	s_add_u32 s0, s20, 0x40000
	global_load_lds_dwordx4 v130, s[20:21]
	s_mov_b32 m0, s37
	s_addc_u32 s1, s21, 0
	s_add_i32 s38, s19, 0x4000
	global_load_lds_dwordx4 v134, s[20:21]
	s_mov_b32 m0, s38
	s_add_i32 s39, s19, 0x6000
	global_load_lds_dwordx4 v130, s[0:1]
	s_mov_b32 m0, s39
	v_mov_b32_e32 v131, v133
	global_load_lds_dwordx4 v134, s[0:1]
	v_mov_b32_e32 v135, v133
	s_cmp_eq_u32 s8, 1
	s_mov_b32 s40, 0
	v_lshl_add_u64 v[8:9], s[22:23], 0, v[132:133]
	v_lshl_add_u64 v[6:7], s[22:23], 0, v[136:137]
	v_lshl_add_u64 v[2:3], s[20:21], 0, v[130:131]
	s_cselect_b64 s[0:1], -1, 0
	s_cmp_lg_u32 s8, 1
	v_lshl_add_u64 v[4:5], s[20:21], 0, v[134:135]
	s_cbranch_scc1 .LBB0_1689
	s_barrier

.LBB0_1699:
	ds_read_b128 v[146:149], v152
	ds_read_b128 v[156:159], v152 offset:1024
	ds_read_b128 v[160:163], v152 offset:2048
	ds_read_b128 v[164:167], v152 offset:3072
	ds_read_b128 v[168:171], v153
	ds_read_b128 v[172:175], v153 offset:1024
	ds_read_b128 v[176:179], v153 offset:2048
	ds_read_b128 v[180:183], v153 offset:3072
	s_add_u32 s22, s20, 0xfffc0080
	s_addc_u32 s23, s21, -1
	s_cmp_eq_u32 s52, 12
	s_cselect_b32 s31, s13, s23
	s_cselect_b32 s30, s48, s22
	s_cselect_b32 s23, s11, s51
	s_cselect_b32 s22, s49, s50
	v_lshl_add_u64 v[216:217], s[20:21], 0, v[138:139]
	s_add_i32 m0, s19, 0xc000
	ds_read_b128 v[184:187], v154
	ds_read_b128 v[188:191], v154 offset:1024
	ds_read_b128 v[192:195], v154 offset:2048
	ds_read_b128 v[196:199], v154 offset:3072
	ds_read_b128 v[200:203], v154 offset:4096
	ds_read_b128 v[204:207], v154 offset:5120
	ds_read_b128 v[208:211], v154 offset:6144
	ds_read_b128 v[212:215], v154 offset:7168
	global_load_lds_dwordx4 v[216:217], off
	v_lshl_add_u64 v[216:217], s[20:21], 0, v[140:141]
	s_add_i32 m0, s19, 0xe000
	s_nop 0
	global_load_lds_dwordx4 v[216:217], off
	s_waitcnt vmcnt(8)
	s_waitcnt lgkmcnt(0)
	s_barrier
	s_waitcnt lgkmcnt(0)
	v_mfma_f32_16x16x32_bf16 v[126:129], v[146:149], v[184:187], v[126:129]
	v_mfma_f32_16x16x32_bf16 v[122:125], v[160:163], v[184:187], v[122:125]
	v_mfma_f32_16x16x32_bf16 v[110:113], v[146:149], v[192:195], v[110:113]
	v_mfma_f32_16x16x32_bf16 v[106:109], v[160:163], v[192:195], v[106:109]
	v_mfma_f32_16x16x32_bf16 v[94:97], v[146:149], v[200:203], v[94:97]
	v_mfma_f32_16x16x32_bf16 v[90:93], v[160:163], v[200:203], v[90:93]
	v_mfma_f32_16x16x32_bf16 v[78:81], v[146:149], v[208:211], v[78:81]
	v_mfma_f32_16x16x32_bf16 v[74:77], v[160:163], v[208:211], v[74:77]
	v_mfma_f32_16x16x32_bf16 v[126:129], v[156:159], v[188:191], v[126:129]
	v_mfma_f32_16x16x32_bf16 v[122:125], v[164:167], v[188:191], v[122:125]
	v_mfma_f32_16x16x32_bf16 v[110:113], v[156:159], v[196:199], v[110:113]
	v_mfma_f32_16x16x32_bf16 v[106:109], v[164:167], v[196:199], v[106:109]
	v_mfma_f32_16x16x32_bf16 v[94:97], v[156:159], v[204:207], v[94:97]
	v_mfma_f32_16x16x32_bf16 v[90:93], v[164:167], v[204:207], v[90:93]
	v_mfma_f32_16x16x32_bf16 v[78:81], v[156:159], v[212:215], v[78:81]
	v_mfma_f32_16x16x32_bf16 v[74:77], v[164:167], v[212:215], v[74:77]
	v_mfma_f32_16x16x32_bf16 v[118:121], v[168:171], v[184:187], v[118:121]
	v_mfma_f32_16x16x32_bf16 v[114:117], v[176:179], v[184:187], v[114:117]
	v_mfma_f32_16x16x32_bf16 v[102:105], v[168:171], v[192:195], v[102:105]
	v_mfma_f32_16x16x32_bf16 v[98:101], v[176:179], v[192:195], v[98:101]
	v_mfma_f32_16x16x32_bf16 v[86:89], v[168:171], v[200:203], v[86:89]
	v_mfma_f32_16x16x32_bf16 v[82:85], v[176:179], v[200:203], v[82:85]
	v_mfma_f32_16x16x32_bf16 v[70:73], v[168:171], v[208:211], v[70:73]
	v_mfma_f32_16x16x32_bf16 v[66:69], v[176:179], v[208:211], v[66:69]
	v_mfma_f32_16x16x32_bf16 v[118:121], v[172:175], v[188:191], v[118:121]
	v_mfma_f32_16x16x32_bf16 v[114:117], v[180:183], v[188:191], v[114:117]
	v_mfma_f32_16x16x32_bf16 v[102:105], v[172:175], v[196:199], v[102:105]
	v_mfma_f32_16x16x32_bf16 v[98:101], v[180:183], v[196:199], v[98:101]
	v_mfma_f32_16x16x32_bf16 v[86:89], v[172:175], v[204:207], v[86:89]
	v_mfma_f32_16x16x32_bf16 v[82:85], v[180:183], v[204:207], v[82:85]
	v_mfma_f32_16x16x32_bf16 v[70:73], v[172:175], v[212:215], v[70:73]
	v_mfma_f32_16x16x32_bf16 v[66:69], v[180:183], v[212:215], v[66:69]
	s_barrier
	s_add_i32 s53, s44, s35
	v_lshl_add_u64 v[216:217], s[22:23], 0, v[132:133]
	s_mov_b32 m0, s53
	ds_read_b128 v[184:187], v154 offset:16384
	ds_read_b128 v[188:191], v154 offset:17408
	ds_read_b128 v[192:195], v154 offset:18432
	ds_read_b128 v[196:199], v154 offset:19456
	ds_read_b128 v[200:203], v154 offset:20480
	ds_read_b128 v[204:207], v154 offset:21504
	ds_read_b128 v[208:211], v154 offset:22528
	ds_read_b128 v[212:215], v154 offset:23552
	global_load_lds_dwordx4 v[216:217], off
	s_add_i32 m0, s53, 0x2000
	s_add_u32 s54, s22, 0x40000
	v_lshl_add_u64 v[218:219], s[22:23], 0, v[136:137]
	s_addc_u32 s55, s23, 0
	s_add_i32 s53, s45, s35
	global_load_lds_dwordx4 v[218:219], off
	v_lshl_add_u64 v[220:221], s[54:55], 0, v[132:133]
	s_mov_b32 m0, s53
	v_lshl_add_u64 v[222:223], s[30:31], 0, v[134:135]
	global_load_lds_dwordx4 v[220:221], off
	v_lshl_add_u64 v[220:221], s[54:55], 0, v[136:137]
	s_add_i32 m0, s53, 0x2000
	s_nop 0
	global_load_lds_dwordx4 v[220:221], off
	v_lshl_add_u64 v[220:221], s[30:31], 0, v[130:131]
	s_mov_b32 m0, s19
	s_nop 0
	global_load_lds_dwordx4 v[220:221], off
	s_mov_b32 m0, s37
	s_nop 0
	global_load_lds_dwordx4 v[222:223], off
	s_waitcnt vmcnt(8)
	s_waitcnt lgkmcnt(0)
	s_barrier
	s_waitcnt lgkmcnt(0)
	v_mfma_f32_16x16x32_bf16 v[62:65], v[146:149], v[184:187], v[62:65]
	v_mfma_f32_16x16x32_bf16 v[58:61], v[160:163], v[184:187], v[58:61]
	v_mfma_f32_16x16x32_bf16 v[46:49], v[146:149], v[192:195], v[46:49]
	v_mfma_f32_16x16x32_bf16 v[42:45], v[160:163], v[192:195], v[42:45]
	v_mfma_f32_16x16x32_bf16 v[30:33], v[146:149], v[200:203], v[30:33]
	v_mfma_f32_16x16x32_bf16 v[26:29], v[160:163], v[200:203], v[26:29]
	v_mfma_f32_16x16x32_bf16 v[14:17], v[146:149], v[208:211], v[14:17]
	v_mfma_f32_16x16x32_bf16 v[10:13], v[160:163], v[208:211], v[10:13]
	v_mfma_f32_16x16x32_bf16 v[62:65], v[156:159], v[188:191], v[62:65]
	v_mfma_f32_16x16x32_bf16 v[58:61], v[164:167], v[188:191], v[58:61]
	v_mfma_f32_16x16x32_bf16 v[46:49], v[156:159], v[196:199], v[46:49]
	v_mfma_f32_16x16x32_bf16 v[42:45], v[164:167], v[196:199], v[42:45]
	v_mfma_f32_16x16x32_bf16 v[30:33], v[156:159], v[204:207], v[30:33]
	v_mfma_f32_16x16x32_bf16 v[26:29], v[164:167], v[204:207], v[26:29]
	v_mfma_f32_16x16x32_bf16 v[14:17], v[156:159], v[212:215], v[14:17]
	v_mfma_f32_16x16x32_bf16 v[10:13], v[164:167], v[212:215], v[10:13]
	v_mfma_f32_16x16x32_bf16 v[54:57], v[168:171], v[184:187], v[54:57]
	v_mfma_f32_16x16x32_bf16 v[50:53], v[176:179], v[184:187], v[50:53]
	v_mfma_f32_16x16x32_bf16 v[38:41], v[168:171], v[192:195], v[38:41]
	v_mfma_f32_16x16x32_bf16 v[34:37], v[176:179], v[192:195], v[34:37]
	v_mfma_f32_16x16x32_bf16 v[22:25], v[168:171], v[200:203], v[22:25]
	v_mfma_f32_16x16x32_bf16 v[18:21], v[176:179], v[200:203], v[18:21]
	v_mfma_f32_16x16x32_bf16 v[6:9], v[168:171], v[208:211], v[6:9]
	v_mfma_f32_16x16x32_bf16 v[2:5], v[176:179], v[208:211], v[2:5]
	v_mfma_f32_16x16x32_bf16 v[54:57], v[172:175], v[188:191], v[54:57]
	v_mfma_f32_16x16x32_bf16 v[50:53], v[180:183], v[188:191], v[50:53]
	v_mfma_f32_16x16x32_bf16 v[38:41], v[172:175], v[196:199], v[38:41]
	v_mfma_f32_16x16x32_bf16 v[34:37], v[180:183], v[196:199], v[34:37]
	v_mfma_f32_16x16x32_bf16 v[22:25], v[172:175], v[204:207], v[22:25]
	v_mfma_f32_16x16x32_bf16 v[18:21], v[180:183], v[204:207], v[18:21]
	v_mfma_f32_16x16x32_bf16 v[6:9], v[172:175], v[212:215], v[6:9]
	v_mfma_f32_16x16x32_bf16 v[2:5], v[180:183], v[212:215], v[2:5]
	s_barrier
	s_add_i32 s53, 0, 0x18000
	v_add_u32_e32 v155, s53, v150
	s_add_i32 s54, 0, 0x1c000
	ds_read_b128 v[146:149], v155
	ds_read_b128 v[156:159], v155 offset:1024
	ds_read_b128 v[160:163], v155 offset:2048
	ds_read_b128 v[164:167], v155 offset:3072
	v_add_u32_e32 v155, s54, v150
	ds_read_b128 v[168:171], v155
	ds_read_b128 v[172:175], v155 offset:1024
	ds_read_b128 v[176:179], v155 offset:2048
	ds_read_b128 v[180:183], v155 offset:3072
	s_add_u32 s30, s30, 0x40000
	s_addc_u32 s31, s31, 0
	s_mov_b32 m0, s38
	v_lshl_add_u64 v[224:225], s[30:31], 0, v[130:131]
	ds_read_b128 v[184:187], v154 offset:32768
	ds_read_b128 v[188:191], v154 offset:33792
	ds_read_b128 v[192:195], v154 offset:34816
	ds_read_b128 v[196:199], v154 offset:35840
	ds_read_b128 v[200:203], v154 offset:36864
	ds_read_b128 v[204:207], v154 offset:37888
	ds_read_b128 v[208:211], v154 offset:38912
	ds_read_b128 v[212:215], v154 offset:39936
	global_load_lds_dwordx4 v[224:225], off
	v_lshl_add_u64 v[224:225], s[30:31], 0, v[134:135]
	s_mov_b32 m0, s39
	s_nop 0
	global_load_lds_dwordx4 v[224:225], off
	s_waitcnt vmcnt(8)
	s_waitcnt lgkmcnt(0)
	s_barrier
	s_waitcnt lgkmcnt(0)
	v_mfma_f32_16x16x32_bf16 v[126:129], v[146:149], v[184:187], v[126:129]
	v_mfma_f32_16x16x32_bf16 v[122:125], v[160:163], v[184:187], v[122:125]
	v_mfma_f32_16x16x32_bf16 v[110:113], v[146:149], v[192:195], v[110:113]
	v_mfma_f32_16x16x32_bf16 v[106:109], v[160:163], v[192:195], v[106:109]
	v_mfma_f32_16x16x32_bf16 v[94:97], v[146:149], v[200:203], v[94:97]
	v_mfma_f32_16x16x32_bf16 v[90:93], v[160:163], v[200:203], v[90:93]
	v_mfma_f32_16x16x32_bf16 v[78:81], v[146:149], v[208:211], v[78:81]
	v_mfma_f32_16x16x32_bf16 v[74:77], v[160:163], v[208:211], v[74:77]
	v_mfma_f32_16x16x32_bf16 v[126:129], v[156:159], v[188:191], v[126:129]
	v_mfma_f32_16x16x32_bf16 v[122:125], v[164:167], v[188:191], v[122:125]
	v_mfma_f32_16x16x32_bf16 v[110:113], v[156:159], v[196:199], v[110:113]
	v_mfma_f32_16x16x32_bf16 v[106:109], v[164:167], v[196:199], v[106:109]
	v_mfma_f32_16x16x32_bf16 v[94:97], v[156:159], v[204:207], v[94:97]
	v_mfma_f32_16x16x32_bf16 v[90:93], v[164:167], v[204:207], v[90:93]
	v_mfma_f32_16x16x32_bf16 v[78:81], v[156:159], v[212:215], v[78:81]
	v_mfma_f32_16x16x32_bf16 v[74:77], v[164:167], v[212:215], v[74:77]
	v_mfma_f32_16x16x32_bf16 v[118:121], v[168:171], v[184:187], v[118:121]
	v_mfma_f32_16x16x32_bf16 v[114:117], v[176:179], v[184:187], v[114:117]
	v_mfma_f32_16x16x32_bf16 v[102:105], v[168:171], v[192:195], v[102:105]
	v_mfma_f32_16x16x32_bf16 v[98:101], v[176:179], v[192:195], v[98:101]
	v_mfma_f32_16x16x32_bf16 v[86:89], v[168:171], v[200:203], v[86:89]
	v_mfma_f32_16x16x32_bf16 v[82:85], v[176:179], v[200:203], v[82:85]
	v_mfma_f32_16x16x32_bf16 v[70:73], v[168:171], v[208:211], v[70:73]
	v_mfma_f32_16x16x32_bf16 v[66:69], v[176:179], v[208:211], v[66:69]
	v_mfma_f32_16x16x32_bf16 v[118:121], v[172:175], v[188:191], v[118:121]
	v_mfma_f32_16x16x32_bf16 v[114:117], v[180:183], v[188:191], v[114:117]
	v_mfma_f32_16x16x32_bf16 v[102:105], v[172:175], v[196:199], v[102:105]
	v_mfma_f32_16x16x32_bf16 v[98:101], v[180:183], v[196:199], v[98:101]
	v_mfma_f32_16x16x32_bf16 v[86:89], v[172:175], v[204:207], v[86:89]
	v_mfma_f32_16x16x32_bf16 v[82:85], v[180:183], v[204:207], v[82:85]
	v_mfma_f32_16x16x32_bf16 v[70:73], v[172:175], v[212:215], v[70:73]
	v_mfma_f32_16x16x32_bf16 v[66:69], v[180:183], v[212:215], v[66:69]
	s_barrier
	s_add_i32 s30, s53, s35
	v_lshl_add_u64 v[216:217], v[216:217], 0, s[6:7]
	s_mov_b32 m0, s30
	ds_read_b128 v[184:187], v154 offset:49152
	ds_read_b128 v[188:191], v154 offset:50176
	ds_read_b128 v[192:195], v154 offset:51200
	ds_read_b128 v[196:199], v154 offset:52224
	ds_read_b128 v[200:203], v154 offset:53248
	ds_read_b128 v[204:207], v154 offset:54272
	ds_read_b128 v[208:211], v154 offset:55296
	ds_read_b128 v[212:215], v154 offset:56320
	global_load_lds_dwordx4 v[216:217], off
	s_add_i32 m0, s30, 0x2000
	s_add_u32 s22, s22, 0x40080
	v_lshl_add_u64 v[216:217], v[218:219], 0, s[6:7]
	s_addc_u32 s23, s23, 0
	s_add_i32 s30, s54, s35
	global_load_lds_dwordx4 v[216:217], off
	v_lshl_add_u64 v[216:217], s[22:23], 0, v[132:133]
	s_mov_b32 m0, s30
	s_nop 0
	global_load_lds_dwordx4 v[216:217], off
	v_lshl_add_u64 v[216:217], s[22:23], 0, v[136:137]
	s_add_i32 m0, s30, 0x2000
	s_nop 0
	global_load_lds_dwordx4 v[216:217], off
	v_lshl_add_u64 v[216:217], v[220:221], 0, s[6:7]
	s_mov_b32 m0, s42
	s_nop 0
	global_load_lds_dwordx4 v[216:217], off
	v_lshl_add_u64 v[216:217], v[222:223], 0, s[6:7]
	s_mov_b32 m0, s43
	s_nop 0
	global_load_lds_dwordx4 v[216:217], off
	s_waitcnt vmcnt(8)
	s_waitcnt lgkmcnt(0)
	s_barrier
	s_waitcnt lgkmcnt(0)
	v_mfma_f32_16x16x32_bf16 v[62:65], v[146:149], v[184:187], v[62:65]
	v_mfma_f32_16x16x32_bf16 v[58:61], v[160:163], v[184:187], v[58:61]
	v_mfma_f32_16x16x32_bf16 v[46:49], v[146:149], v[192:195], v[46:49]
	v_mfma_f32_16x16x32_bf16 v[42:45], v[160:163], v[192:195], v[42:45]
	v_mfma_f32_16x16x32_bf16 v[30:33], v[146:149], v[200:203], v[30:33]
	v_mfma_f32_16x16x32_bf16 v[26:29], v[160:163], v[200:203], v[26:29]
	v_mfma_f32_16x16x32_bf16 v[14:17], v[146:149], v[208:211], v[14:17]
	v_mfma_f32_16x16x32_bf16 v[10:13], v[160:163], v[208:211], v[10:13]
	v_mfma_f32_16x16x32_bf16 v[62:65], v[156:159], v[188:191], v[62:65]
	v_mfma_f32_16x16x32_bf16 v[58:61], v[164:167], v[188:191], v[58:61]
	v_mfma_f32_16x16x32_bf16 v[46:49], v[156:159], v[196:199], v[46:49]
	v_mfma_f32_16x16x32_bf16 v[42:45], v[164:167], v[196:199], v[42:45]
	v_mfma_f32_16x16x32_bf16 v[30:33], v[156:159], v[204:207], v[30:33]
	v_mfma_f32_16x16x32_bf16 v[26:29], v[164:167], v[204:207], v[26:29]
	v_mfma_f32_16x16x32_bf16 v[14:17], v[156:159], v[212:215], v[14:17]
	v_mfma_f32_16x16x32_bf16 v[10:13], v[164:167], v[212:215], v[10:13]
	v_mfma_f32_16x16x32_bf16 v[54:57], v[168:171], v[184:187], v[54:57]
	v_mfma_f32_16x16x32_bf16 v[50:53], v[176:179], v[184:187], v[50:53]
	v_mfma_f32_16x16x32_bf16 v[38:41], v[168:171], v[192:195], v[38:41]
	v_mfma_f32_16x16x32_bf16 v[34:37], v[176:179], v[192:195], v[34:37]
	v_mfma_f32_16x16x32_bf16 v[22:25], v[168:171], v[200:203], v[22:25]
	v_mfma_f32_16x16x32_bf16 v[18:21], v[176:179], v[200:203], v[18:21]
	v_mfma_f32_16x16x32_bf16 v[6:9], v[168:171], v[208:211], v[6:9]
	v_mfma_f32_16x16x32_bf16 v[2:5], v[176:179], v[208:211], v[2:5]
	v_mfma_f32_16x16x32_bf16 v[54:57], v[172:175], v[188:191], v[54:57]
	v_mfma_f32_16x16x32_bf16 v[50:53], v[180:183], v[188:191], v[50:53]
	v_mfma_f32_16x16x32_bf16 v[38:41], v[172:175], v[196:199], v[38:41]
	v_mfma_f32_16x16x32_bf16 v[34:37], v[180:183], v[196:199], v[34:37]
	v_mfma_f32_16x16x32_bf16 v[22:25], v[172:175], v[204:207], v[22:25]
	v_mfma_f32_16x16x32_bf16 v[18:21], v[180:183], v[204:207], v[18:21]
	v_mfma_f32_16x16x32_bf16 v[6:9], v[172:175], v[212:215], v[6:9]
	v_mfma_f32_16x16x32_bf16 v[2:5], v[180:183], v[212:215], v[2:5]
	s_barrier
	s_add_i32 s52, s52, 2
	s_add_u32 s20, s20, 0x100
	s_addc_u32 s21, s21, 0
	s_add_u32 s50, s50, 0x100
	s_addc_u32 s51, s51, 0
	s_cmp_gt_u32 s52, 13
	s_cbranch_scc0 .LBB0_1699
	s_and_b64 vcc, exec, s[8:9]
	s_cbranch_vccz .LBB0_1702
	s_barrier

.LBB0_1760:
	s_setprio 0
	s_cmp_lt_i32 s90, 12
	s_cselect_b64 s[0:1], -1, 0
	s_cmp_gt_i32 s91, 11
	s_cselect_b64 s[2:3], -1, 0
	s_and_b64 s[0:1], s[0:1], s[2:3]
	s_andn2_b64 vcc, exec, s[0:1]
	s_cbranch_vccnz .LBB0_1856
	s_cmpk_lt_u32 s80, 0x100
	s_cbranch_scc1 .Lprio_skip_5
	s_setprio 1
.Lprio_skip_5:
	s_cmpk_gt_i32 s24, 0xff
	v_readfirstlane_b32 s8, v0
	v_mbcnt_lo_u32_b32 v1, -1, 0
	v_mbcnt_hi_u32_b32 v1, -1, v1
	s_cbranch_scc0 .LBB0_1767
	s_mov_b64 s[2:3], 0
	s_cmpk_lt_u32 s24, 0x158
	s_mov_b64 s[0:1], 0
	s_cbranch_scc0 .LBB0_1764
	s_and_b32 s0, s24, 0xff
	s_mul_i32 s1, s0, 0x75
	s_lshr_b32 s1, s1, 8
	s_sub_i32 s4, s24, s1
	s_bfe_u32 s4, s4, 0x70001
	s_add_i32 s4, s4, s1
	s_bfe_u32 s1, s4, 0x50003
	s_mul_i32 s4, s1, 11
	s_sub_i32 s4, s24, s4
	s_add_i32 s5, s1, -4
	s_cmp_lt_u32 s0, 44
	s_cselect_b32 s73, s1, s5
	s_cmp_gt_u32 s0, 43
	s_cselect_b32 s74, 0x41, 64
	s_lshl_b32 s0, s4, 2
	s_and_b32 s72, s0, 0xfc
	s_mov_b64 s[0:1], -1
	s_mov_b32 s75, 4
	s_and_b64 vcc, exec, s[2:3]
	s_cbranch_vccz .LBB0_1768
	s_branch .LBB0_1765

.LBB0_1788:
	ds_read_b128 v[142:145], v149
	ds_read_b128 v[152:155], v149 offset:1024
	ds_read_b128 v[156:159], v149 offset:2048
	ds_read_b128 v[160:163], v149 offset:3072
	ds_read_b128 v[164:167], v150
	ds_read_b128 v[168:171], v150 offset:1024
	ds_read_b128 v[172:175], v150 offset:2048
	ds_read_b128 v[176:179], v150 offset:3072
	s_add_u32 s20, s18, 0xfff50080
	s_addc_u32 s21, s19, -1
	s_cmp_eq_u32 s75, s77
	s_cselect_b32 s23, s15, s21
	s_cselect_b32 s22, s14, s20
	s_cselect_b32 s21, s17, s76
	s_cselect_b32 s20, s16, s13
	v_lshl_add_u64 v[212:213], s[18:19], 0, v[136:137]
	s_add_i32 m0, s34, 0xc000
	ds_read_b128 v[180:183], v151
	ds_read_b128 v[184:187], v151 offset:1024
	ds_read_b128 v[188:191], v151 offset:2048
	ds_read_b128 v[192:195], v151 offset:3072
	ds_read_b128 v[196:199], v151 offset:4096
	ds_read_b128 v[200:203], v151 offset:5120
	ds_read_b128 v[204:207], v151 offset:6144
	ds_read_b128 v[208:211], v151 offset:7168
	global_load_lds_dwordx4 v[212:213], off
	v_lshl_add_u64 v[212:213], s[18:19], 0, v[138:139]
	s_add_i32 m0, s34, 0xe000
	s_nop 0
	global_load_lds_dwordx4 v[212:213], off
	s_waitcnt vmcnt(8)
	s_waitcnt lgkmcnt(0)
	s_barrier
	s_waitcnt lgkmcnt(0)
	v_mfma_f32_16x16x32_bf16 v[124:127], v[142:145], v[180:183], v[124:127]
	v_mfma_f32_16x16x32_bf16 v[120:123], v[156:159], v[180:183], v[120:123]
	v_mfma_f32_16x16x32_bf16 v[116:119], v[142:145], v[188:191], v[116:119]
	v_mfma_f32_16x16x32_bf16 v[108:111], v[156:159], v[188:191], v[108:111]
	v_mfma_f32_16x16x32_bf16 v[100:103], v[142:145], v[196:199], v[100:103]
	v_mfma_f32_16x16x32_bf16 v[92:95], v[156:159], v[196:199], v[92:95]
	v_mfma_f32_16x16x32_bf16 v[84:87], v[142:145], v[204:207], v[84:87]
	v_mfma_f32_16x16x32_bf16 v[76:79], v[156:159], v[204:207], v[76:79]
	v_mfma_f32_16x16x32_bf16 v[124:127], v[152:155], v[184:187], v[124:127]
	v_mfma_f32_16x16x32_bf16 v[120:123], v[160:163], v[184:187], v[120:123]
	v_mfma_f32_16x16x32_bf16 v[116:119], v[152:155], v[192:195], v[116:119]
	v_mfma_f32_16x16x32_bf16 v[108:111], v[160:163], v[192:195], v[108:111]
	v_mfma_f32_16x16x32_bf16 v[100:103], v[152:155], v[200:203], v[100:103]
	v_mfma_f32_16x16x32_bf16 v[92:95], v[160:163], v[200:203], v[92:95]
	v_mfma_f32_16x16x32_bf16 v[84:87], v[152:155], v[208:211], v[84:87]
	v_mfma_f32_16x16x32_bf16 v[76:79], v[160:163], v[208:211], v[76:79]
	v_mfma_f32_16x16x32_bf16 v[112:115], v[164:167], v[180:183], v[112:115]
	v_mfma_f32_16x16x32_bf16 v[104:107], v[172:175], v[180:183], v[104:107]
	v_mfma_f32_16x16x32_bf16 v[96:99], v[164:167], v[188:191], v[96:99]
	v_mfma_f32_16x16x32_bf16 v[88:91], v[172:175], v[188:191], v[88:91]
	v_mfma_f32_16x16x32_bf16 v[80:83], v[164:167], v[196:199], v[80:83]
	v_mfma_f32_16x16x32_bf16 v[72:75], v[172:175], v[196:199], v[72:75]
	v_mfma_f32_16x16x32_bf16 v[68:71], v[164:167], v[204:207], v[68:71]
	v_mfma_f32_16x16x32_bf16 v[64:67], v[172:175], v[204:207], v[64:67]
	v_mfma_f32_16x16x32_bf16 v[112:115], v[168:171], v[184:187], v[112:115]
	v_mfma_f32_16x16x32_bf16 v[104:107], v[176:179], v[184:187], v[104:107]
	v_mfma_f32_16x16x32_bf16 v[96:99], v[168:171], v[192:195], v[96:99]
	v_mfma_f32_16x16x32_bf16 v[88:91], v[176:179], v[192:195], v[88:91]
	v_mfma_f32_16x16x32_bf16 v[80:83], v[168:171], v[200:203], v[80:83]
	v_mfma_f32_16x16x32_bf16 v[72:75], v[176:179], v[200:203], v[72:75]
	v_mfma_f32_16x16x32_bf16 v[68:71], v[168:171], v[208:211], v[68:71]
	v_mfma_f32_16x16x32_bf16 v[64:67], v[176:179], v[208:211], v[64:67]
	s_barrier
	s_add_i32 s78, s48, s31
	v_lshl_add_u64 v[212:213], s[20:21], 0, v[130:131]
	s_mov_b32 m0, s78
	ds_read_b128 v[180:183], v151 offset:16384
	ds_read_b128 v[184:187], v151 offset:17408
	ds_read_b128 v[188:191], v151 offset:18432
	ds_read_b128 v[192:195], v151 offset:19456
	ds_read_b128 v[196:199], v151 offset:20480
	ds_read_b128 v[200:203], v151 offset:21504
	ds_read_b128 v[204:207], v151 offset:22528
	ds_read_b128 v[208:211], v151 offset:23552
	global_load_lds_dwordx4 v[212:213], off
	s_add_i32 m0, s78, 0x2000
	s_add_u32 s78, s20, 0xb0000
	v_lshl_add_u64 v[214:215], s[20:21], 0, v[134:135]
	s_addc_u32 s79, s21, 0
	s_add_i32 s80, s49, s31
	global_load_lds_dwordx4 v[214:215], off
	v_lshl_add_u64 v[216:217], s[78:79], 0, v[130:131]
	s_mov_b32 m0, s80
	v_lshl_add_u64 v[218:219], s[22:23], 0, v[132:133]
	global_load_lds_dwordx4 v[216:217], off
	v_lshl_add_u64 v[216:217], s[78:79], 0, v[134:135]
	s_add_i32 m0, s80, 0x2000
	s_nop 0
	global_load_lds_dwordx4 v[216:217], off
	v_lshl_add_u64 v[216:217], s[22:23], 0, v[128:129]
	s_mov_b32 m0, s34
	s_nop 0
	global_load_lds_dwordx4 v[216:217], off
	s_mov_b32 m0, s35
	s_nop 0
	global_load_lds_dwordx4 v[218:219], off
	s_waitcnt vmcnt(8)
	s_waitcnt lgkmcnt(0)
	s_barrier
	s_waitcnt lgkmcnt(0)
	v_mfma_f32_16x16x32_bf16 v[60:63], v[142:145], v[180:183], v[60:63]
	v_mfma_f32_16x16x32_bf16 v[56:59], v[156:159], v[180:183], v[56:59]
	v_mfma_f32_16x16x32_bf16 v[52:55], v[142:145], v[188:191], v[52:55]
	v_mfma_f32_16x16x32_bf16 v[44:47], v[156:159], v[188:191], v[44:47]
	v_mfma_f32_16x16x32_bf16 v[36:39], v[142:145], v[196:199], v[36:39]
	v_mfma_f32_16x16x32_bf16 v[28:31], v[156:159], v[196:199], v[28:31]
	v_mfma_f32_16x16x32_bf16 v[20:23], v[142:145], v[204:207], v[20:23]
	v_mfma_f32_16x16x32_bf16 v[12:15], v[156:159], v[204:207], v[12:15]
	v_mfma_f32_16x16x32_bf16 v[60:63], v[152:155], v[184:187], v[60:63]
	v_mfma_f32_16x16x32_bf16 v[56:59], v[160:163], v[184:187], v[56:59]
	v_mfma_f32_16x16x32_bf16 v[52:55], v[152:155], v[192:195], v[52:55]
	v_mfma_f32_16x16x32_bf16 v[44:47], v[160:163], v[192:195], v[44:47]
	v_mfma_f32_16x16x32_bf16 v[36:39], v[152:155], v[200:203], v[36:39]
	v_mfma_f32_16x16x32_bf16 v[28:31], v[160:163], v[200:203], v[28:31]
	v_mfma_f32_16x16x32_bf16 v[20:23], v[152:155], v[208:211], v[20:23]
	v_mfma_f32_16x16x32_bf16 v[12:15], v[160:163], v[208:211], v[12:15]
	v_mfma_f32_16x16x32_bf16 v[48:51], v[164:167], v[180:183], v[48:51]
	v_mfma_f32_16x16x32_bf16 v[40:43], v[172:175], v[180:183], v[40:43]
	v_mfma_f32_16x16x32_bf16 v[32:35], v[164:167], v[188:191], v[32:35]
	v_mfma_f32_16x16x32_bf16 v[24:27], v[172:175], v[188:191], v[24:27]
	v_mfma_f32_16x16x32_bf16 v[16:19], v[164:167], v[196:199], v[16:19]
	v_mfma_f32_16x16x32_bf16 v[8:11], v[172:175], v[196:199], v[8:11]
	v_mfma_f32_16x16x32_bf16 v[4:7], v[164:167], v[204:207], v[4:7]
	v_mfma_f32_16x16x32_bf16 v[0:3], v[172:175], v[204:207], v[0:3]
	v_mfma_f32_16x16x32_bf16 v[48:51], v[168:171], v[184:187], v[48:51]
	v_mfma_f32_16x16x32_bf16 v[40:43], v[176:179], v[184:187], v[40:43]
	v_mfma_f32_16x16x32_bf16 v[32:35], v[168:171], v[192:195], v[32:35]
	v_mfma_f32_16x16x32_bf16 v[24:27], v[176:179], v[192:195], v[24:27]
	v_mfma_f32_16x16x32_bf16 v[16:19], v[168:171], v[200:203], v[16:19]
	v_mfma_f32_16x16x32_bf16 v[8:11], v[176:179], v[200:203], v[8:11]
	v_mfma_f32_16x16x32_bf16 v[4:7], v[168:171], v[208:211], v[4:7]
	v_mfma_f32_16x16x32_bf16 v[0:3], v[176:179], v[208:211], v[0:3]
	s_barrier
	s_add_i32 s78, 0, 0x18000
	s_add_i32 s79, 0, 0x1c000
	v_add_u32_e32 v160, s78, v147
	v_add_u32_e32 v176, s79, v147
	ds_read_b128 v[142:145], v160
	ds_read_b128 v[152:155], v160 offset:1024
	ds_read_b128 v[156:159], v160 offset:2048
	ds_read_b128 v[160:163], v160 offset:3072
	ds_read_b128 v[164:167], v176
	ds_read_b128 v[168:171], v176 offset:1024
	ds_read_b128 v[172:175], v176 offset:2048
	ds_read_b128 v[176:179], v176 offset:3072
	s_add_u32 s22, s22, 0xb0000
	s_addc_u32 s23, s23, 0
	s_mov_b32 m0, s36
	v_lshl_add_u64 v[220:221], s[22:23], 0, v[128:129]
	ds_read_b128 v[180:183], v151 offset:32768
	ds_read_b128 v[184:187], v151 offset:33792
	ds_read_b128 v[188:191], v151 offset:34816
	ds_read_b128 v[192:195], v151 offset:35840
	ds_read_b128 v[196:199], v151 offset:36864
	ds_read_b128 v[200:203], v151 offset:37888
	ds_read_b128 v[204:207], v151 offset:38912
	ds_read_b128 v[208:211], v151 offset:39936
	global_load_lds_dwordx4 v[220:221], off
	v_lshl_add_u64 v[220:221], s[22:23], 0, v[132:133]
	s_mov_b32 m0, s37
	s_nop 0
	global_load_lds_dwordx4 v[220:221], off
	s_waitcnt vmcnt(8)
	s_waitcnt lgkmcnt(0)
	s_barrier
	s_waitcnt lgkmcnt(0)
	v_mfma_f32_16x16x32_bf16 v[124:127], v[142:145], v[180:183], v[124:127]
	v_mfma_f32_16x16x32_bf16 v[120:123], v[156:159], v[180:183], v[120:123]
	v_mfma_f32_16x16x32_bf16 v[116:119], v[142:145], v[188:191], v[116:119]
	v_mfma_f32_16x16x32_bf16 v[108:111], v[156:159], v[188:191], v[108:111]
	v_mfma_f32_16x16x32_bf16 v[100:103], v[142:145], v[196:199], v[100:103]
	v_mfma_f32_16x16x32_bf16 v[92:95], v[156:159], v[196:199], v[92:95]
	v_mfma_f32_16x16x32_bf16 v[84:87], v[142:145], v[204:207], v[84:87]
	v_mfma_f32_16x16x32_bf16 v[76:79], v[156:159], v[204:207], v[76:79]
	v_mfma_f32_16x16x32_bf16 v[124:127], v[152:155], v[184:187], v[124:127]
	v_mfma_f32_16x16x32_bf16 v[120:123], v[160:163], v[184:187], v[120:123]
	v_mfma_f32_16x16x32_bf16 v[116:119], v[152:155], v[192:195], v[116:119]
	v_mfma_f32_16x16x32_bf16 v[108:111], v[160:163], v[192:195], v[108:111]
	v_mfma_f32_16x16x32_bf16 v[100:103], v[152:155], v[200:203], v[100:103]
	v_mfma_f32_16x16x32_bf16 v[92:95], v[160:163], v[200:203], v[92:95]
	v_mfma_f32_16x16x32_bf16 v[84:87], v[152:155], v[208:211], v[84:87]
	v_mfma_f32_16x16x32_bf16 v[76:79], v[160:163], v[208:211], v[76:79]
	v_mfma_f32_16x16x32_bf16 v[112:115], v[164:167], v[180:183], v[112:115]
	v_mfma_f32_16x16x32_bf16 v[104:107], v[172:175], v[180:183], v[104:107]
	v_mfma_f32_16x16x32_bf16 v[96:99], v[164:167], v[188:191], v[96:99]
	v_mfma_f32_16x16x32_bf16 v[88:91], v[172:175], v[188:191], v[88:91]
	v_mfma_f32_16x16x32_bf16 v[80:83], v[164:167], v[196:199], v[80:83]
	v_mfma_f32_16x16x32_bf16 v[72:75], v[172:175], v[196:199], v[72:75]
	v_mfma_f32_16x16x32_bf16 v[68:71], v[164:167], v[204:207], v[68:71]
	v_mfma_f32_16x16x32_bf16 v[64:67], v[172:175], v[204:207], v[64:67]
	v_mfma_f32_16x16x32_bf16 v[112:115], v[168:171], v[184:187], v[112:115]
	v_mfma_f32_16x16x32_bf16 v[104:107], v[176:179], v[184:187], v[104:107]
	v_mfma_f32_16x16x32_bf16 v[96:99], v[168:171], v[192:195], v[96:99]
	v_mfma_f32_16x16x32_bf16 v[88:91], v[176:179], v[192:195], v[88:91]
	v_mfma_f32_16x16x32_bf16 v[80:83], v[168:171], v[200:203], v[80:83]
	v_mfma_f32_16x16x32_bf16 v[72:75], v[176:179], v[200:203], v[72:75]
	v_mfma_f32_16x16x32_bf16 v[68:71], v[168:171], v[208:211], v[68:71]
	v_mfma_f32_16x16x32_bf16 v[64:67], v[176:179], v[208:211], v[64:67]
	s_barrier
	s_add_i32 s22, s78, s31
	v_lshl_add_u64 v[212:213], v[212:213], 0, s[6:7]
	s_mov_b32 m0, s22
	ds_read_b128 v[180:183], v151 offset:49152
	ds_read_b128 v[184:187], v151 offset:50176
	ds_read_b128 v[188:191], v151 offset:51200
	ds_read_b128 v[192:195], v151 offset:52224
	ds_read_b128 v[196:199], v151 offset:53248
	ds_read_b128 v[200:203], v151 offset:54272
	ds_read_b128 v[204:207], v151 offset:55296
	ds_read_b128 v[208:211], v151 offset:56320
	global_load_lds_dwordx4 v[212:213], off
	s_add_i32 m0, s22, 0x2000
	s_add_u32 s20, s20, 0xb0080
	v_lshl_add_u64 v[212:213], v[214:215], 0, s[6:7]
	s_addc_u32 s21, s21, 0
	s_add_i32 s22, s79, s31
	global_load_lds_dwordx4 v[212:213], off
	v_lshl_add_u64 v[212:213], s[20:21], 0, v[130:131]
	s_mov_b32 m0, s22
	s_nop 0
	global_load_lds_dwordx4 v[212:213], off
	v_lshl_add_u64 v[212:213], s[20:21], 0, v[134:135]
	s_add_i32 m0, s22, 0x2000
	s_nop 0
	global_load_lds_dwordx4 v[212:213], off
	v_lshl_add_u64 v[212:213], v[216:217], 0, s[6:7]
	s_mov_b32 m0, s42
	s_nop 0
	global_load_lds_dwordx4 v[212:213], off
	v_lshl_add_u64 v[212:213], v[218:219], 0, s[6:7]
	s_mov_b32 m0, s43
	s_nop 0
	global_load_lds_dwordx4 v[212:213], off
	s_waitcnt vmcnt(8)
	s_waitcnt lgkmcnt(0)
	s_barrier
	s_waitcnt lgkmcnt(0)
	v_mfma_f32_16x16x32_bf16 v[60:63], v[142:145], v[180:183], v[60:63]
	v_mfma_f32_16x16x32_bf16 v[56:59], v[156:159], v[180:183], v[56:59]
	v_mfma_f32_16x16x32_bf16 v[52:55], v[142:145], v[188:191], v[52:55]
	v_mfma_f32_16x16x32_bf16 v[44:47], v[156:159], v[188:191], v[44:47]
	v_mfma_f32_16x16x32_bf16 v[36:39], v[142:145], v[196:199], v[36:39]
	v_mfma_f32_16x16x32_bf16 v[28:31], v[156:159], v[196:199], v[28:31]
	v_mfma_f32_16x16x32_bf16 v[20:23], v[142:145], v[204:207], v[20:23]
	v_mfma_f32_16x16x32_bf16 v[12:15], v[156:159], v[204:207], v[12:15]
	v_mfma_f32_16x16x32_bf16 v[60:63], v[152:155], v[184:187], v[60:63]
	v_mfma_f32_16x16x32_bf16 v[56:59], v[160:163], v[184:187], v[56:59]
	v_mfma_f32_16x16x32_bf16 v[52:55], v[152:155], v[192:195], v[52:55]
	v_mfma_f32_16x16x32_bf16 v[44:47], v[160:163], v[192:195], v[44:47]
	v_mfma_f32_16x16x32_bf16 v[36:39], v[152:155], v[200:203], v[36:39]
	v_mfma_f32_16x16x32_bf16 v[28:31], v[160:163], v[200:203], v[28:31]
	v_mfma_f32_16x16x32_bf16 v[20:23], v[152:155], v[208:211], v[20:23]
	v_mfma_f32_16x16x32_bf16 v[12:15], v[160:163], v[208:211], v[12:15]
	v_mfma_f32_16x16x32_bf16 v[48:51], v[164:167], v[180:183], v[48:51]
	v_mfma_f32_16x16x32_bf16 v[40:43], v[172:175], v[180:183], v[40:43]
	v_mfma_f32_16x16x32_bf16 v[32:35], v[164:167], v[188:191], v[32:35]
	v_mfma_f32_16x16x32_bf16 v[24:27], v[172:175], v[188:191], v[24:27]
	v_mfma_f32_16x16x32_bf16 v[16:19], v[164:167], v[196:199], v[16:19]
	v_mfma_f32_16x16x32_bf16 v[8:11], v[172:175], v[196:199], v[8:11]
	v_mfma_f32_16x16x32_bf16 v[4:7], v[164:167], v[204:207], v[4:7]
	v_mfma_f32_16x16x32_bf16 v[0:3], v[172:175], v[204:207], v[0:3]
	v_mfma_f32_16x16x32_bf16 v[48:51], v[168:171], v[184:187], v[48:51]
	v_mfma_f32_16x16x32_bf16 v[40:43], v[176:179], v[184:187], v[40:43]
	v_mfma_f32_16x16x32_bf16 v[32:35], v[168:171], v[192:195], v[32:35]
	v_mfma_f32_16x16x32_bf16 v[24:27], v[176:179], v[192:195], v[24:27]
	v_mfma_f32_16x16x32_bf16 v[16:19], v[168:171], v[200:203], v[16:19]
	v_mfma_f32_16x16x32_bf16 v[8:11], v[176:179], v[200:203], v[8:11]
	v_mfma_f32_16x16x32_bf16 v[4:7], v[168:171], v[208:211], v[4:7]
	v_mfma_f32_16x16x32_bf16 v[0:3], v[176:179], v[208:211], v[0:3]
	s_barrier
	s_add_i32 s20, s77, 2
	s_add_u32 s18, s18, 0x100
	s_addc_u32 s19, s19, 0
	s_add_u32 s13, s13, 0x100
	s_addc_u32 s76, s76, 0
	s_cmp_ge_i32 s77, s75
	s_mov_b32 s77, s20
	s_cbranch_scc0 .LBB0_1788
	s_and_b64 vcc, exec, s[8:9]
	s_cbranch_vccz .LBB0_1791
	s_barrier

.LBB0_1856:
	s_setprio 0
	s_cmp_lt_i32 s90, 13
	s_cselect_b64 s[0:1], -1, 0
	s_cmp_gt_i32 s91, 12
	s_cselect_b64 s[2:3], -1, 0
	s_and_b64 s[0:1], s[0:1], s[2:3]
	s_andn2_b64 vcc, exec, s[0:1]
	s_cbranch_vccnz .LBB0_1891
	s_lshl_b32 s0, s82, 3
	s_add_i32 s0, s0, s83
	s_cmpk_gt_i32 s0, 0x41ff
	s_waitcnt vmcnt(0)
	v_mbcnt_lo_u32_b32 v68, -1, 0
	v_mbcnt_hi_u32_b32 v68, -1, v68
	s_cbranch_scc1 .LBB0_1891
	s_waitcnt lgkmcnt(0)
	s_mov_b32 s4, s0
	v_mbcnt_lo_u32_b32 v1, -1, 0
	v_mbcnt_hi_u32_b32 v1, -1, v1
	v_lshlrev_b32_e32 v19, 4, v1
	v_lshlrev_b32_e32 v1, 3, v1
	s_add_u32 s14, s66, 0x5000
	s_addc_u32 s15, s67, 0
	global_load_dwordx4 v[2:5], v19, s[14:15] offset:0
	global_load_dwordx4 v[6:9], v19, s[14:15] offset:1024
	global_load_dwordx4 v[10:13], v19, s[14:15] offset:2048
	global_load_dwordx4 v[14:17], v19, s[14:15] offset:3072
	s_mov_b32 s34, 0xffff0000
	s_mov_b32 s35, 0xf800000
	v_mov_b32_e32 v69, 0x358637bd
	v_mov_b32_e32 v80, 0x260
	s_lshl_b32 s23, s33, 3
	s_lshl_b32 s20, s33, 14
	s_lshl_b32 s21, s33, 15
	s_mul_i32 s22, s23, 3
	s_sub_i32 s22, 0x4000, s22
	v_readlane_b32 s2, v255, 37
	v_readlane_b32 s3, v255, 38
	s_mov_b32 s5, s4
	s_lshl_b32 s36, s4, 11
	s_lshl_b32 s37, s4, 12
	s_add_u32 s6, s26, 0xae00000
	s_addc_u32 s7, s27, 0
	s_add_u32 s6, s6, s36
	s_addc_u32 s7, s7, 0
	s_add_u32 s8, s26, 0xf000000
	s_addc_u32 s9, s27, 0
	s_add_u32 s8, s8, s36
	s_addc_u32 s9, s9, 0
	s_add_u32 s10, s2, s37
	s_addc_u32 s11, s3, 0
